# v21: v4 plus loop-edge edit in all eight GEMM K-loops (loop-back barrier moved behind the counter/pointer/exit-test SALU block)
# baseline (speedup 1.0000x reference)
.LBB0_143:
	s_waitcnt vmcnt(0)
	ds_read_b128 v[24:27], v179
	ds_read_b128 v[28:31], v179 offset:1024
	ds_read_b128 v[44:47], v179 offset:2048
	ds_read_b128 v[52:55], v179 offset:3072
	ds_read_b128 v[144:147], v180
	ds_read_b128 v[148:151], v180 offset:1024
	ds_read_b128 v[170:173], v180 offset:2048
	ds_read_b128 v[184:187], v180 offset:3072
	s_add_u32 s24, s6, 0xfffc0080
	s_addc_u32 s25, s7, -1
	s_cmp_eq_u32 s82, 12
	s_cselect_b32 s27, s1, s25
	s_cselect_b32 s26, s0, s24
	s_cselect_b32 s25, s23, s21
	s_cselect_b32 s24, s22, s9
	v_lshl_add_u64 v[174:175], s[6:7], 0, v[162:163]
	s_add_i32 m0, s29, 0xc000
	ds_read_b128 v[188:191], v181
	ds_read_b128 v[192:195], v181 offset:1024
	ds_read_b128 v[196:199], v181 offset:2048
	ds_read_b128 v[200:203], v181 offset:3072
	ds_read_b128 v[204:207], v181 offset:4096
	ds_read_b128 v[210:213], v181 offset:5120
	ds_read_b128 v[214:217], v181 offset:6144
	ds_read_b128 v[218:221], v181 offset:7168
	global_load_lds_dwordx4 v[174:175], off
	v_lshl_add_u64 v[174:175], s[6:7], 0, v[164:165]
	s_add_i32 m0, s29, 0xe000
	s_nop 0
	global_load_lds_dwordx4 v[174:175], off
	s_waitcnt vmcnt(8)
	s_waitcnt lgkmcnt(0)
	s_barrier
	s_setprio 1
	s_waitcnt lgkmcnt(0)
	v_mfma_f32_16x16x32_bf16 v[140:143], v[24:27], v[188:191], v[140:143]
	v_mfma_f32_16x16x32_bf16 v[136:139], v[44:47], v[188:191], v[136:139]
	v_mfma_f32_16x16x32_bf16 v[124:127], v[24:27], v[196:199], v[124:127]
	v_mfma_f32_16x16x32_bf16 v[120:123], v[44:47], v[196:199], v[120:123]
	v_mfma_f32_16x16x32_bf16 v[108:111], v[24:27], v[204:207], v[108:111]
	v_mfma_f32_16x16x32_bf16 v[104:107], v[44:47], v[204:207], v[104:107]
	v_mfma_f32_16x16x32_bf16 v[92:95], v[24:27], v[214:217], v[92:95]
	v_mfma_f32_16x16x32_bf16 v[88:91], v[44:47], v[214:217], v[88:91]
	v_mfma_f32_16x16x32_bf16 v[140:143], v[28:31], v[192:195], v[140:143]
	v_mfma_f32_16x16x32_bf16 v[136:139], v[52:55], v[192:195], v[136:139]
	v_mfma_f32_16x16x32_bf16 v[124:127], v[28:31], v[200:203], v[124:127]
	v_mfma_f32_16x16x32_bf16 v[120:123], v[52:55], v[200:203], v[120:123]
	v_mfma_f32_16x16x32_bf16 v[108:111], v[28:31], v[210:213], v[108:111]
	v_mfma_f32_16x16x32_bf16 v[104:107], v[52:55], v[210:213], v[104:107]
	v_mfma_f32_16x16x32_bf16 v[92:95], v[28:31], v[218:221], v[92:95]
	v_mfma_f32_16x16x32_bf16 v[88:91], v[52:55], v[218:221], v[88:91]
	s_setprio 0
	s_setprio 1
	v_mfma_f32_16x16x32_bf16 v[132:135], v[144:147], v[188:191], v[132:135]
	v_mfma_f32_16x16x32_bf16 v[128:131], v[170:173], v[188:191], v[128:131]
	v_mfma_f32_16x16x32_bf16 v[116:119], v[144:147], v[196:199], v[116:119]
	v_mfma_f32_16x16x32_bf16 v[112:115], v[170:173], v[196:199], v[112:115]
	v_mfma_f32_16x16x32_bf16 v[100:103], v[144:147], v[204:207], v[100:103]
	v_mfma_f32_16x16x32_bf16 v[96:99], v[170:173], v[204:207], v[96:99]
	v_mfma_f32_16x16x32_bf16 v[84:87], v[144:147], v[214:217], v[84:87]
	v_mfma_f32_16x16x32_bf16 v[80:83], v[170:173], v[214:217], v[80:83]
	v_mfma_f32_16x16x32_bf16 v[132:135], v[148:151], v[192:195], v[132:135]
	v_mfma_f32_16x16x32_bf16 v[128:131], v[184:187], v[192:195], v[128:131]
	v_mfma_f32_16x16x32_bf16 v[116:119], v[148:151], v[200:203], v[116:119]
	v_mfma_f32_16x16x32_bf16 v[112:115], v[184:187], v[200:203], v[112:115]
	v_mfma_f32_16x16x32_bf16 v[100:103], v[148:151], v[210:213], v[100:103]
	v_mfma_f32_16x16x32_bf16 v[96:99], v[184:187], v[210:213], v[96:99]
	v_mfma_f32_16x16x32_bf16 v[84:87], v[148:151], v[218:221], v[84:87]
	v_mfma_f32_16x16x32_bf16 v[80:83], v[184:187], v[218:221], v[80:83]
	s_setprio 0
	s_barrier
	s_add_i32 s83, s96, s28
	v_lshl_add_u64 v[174:175], s[24:25], 0, v[154:155]
	s_mov_b32 m0, s83
	ds_read_b128 v[188:191], v181 offset:16384
	ds_read_b128 v[192:195], v181 offset:17408
	ds_read_b128 v[196:199], v181 offset:18432
	ds_read_b128 v[200:203], v181 offset:19456
	ds_read_b128 v[204:207], v181 offset:20480
	ds_read_b128 v[210:213], v181 offset:21504
	ds_read_b128 v[214:217], v181 offset:22528
	ds_read_b128 v[218:221], v181 offset:23552
	global_load_lds_dwordx4 v[174:175], off
	s_add_i32 m0, s83, 0x2000
	s_add_u32 s84, s24, 0x40000
	v_lshl_add_u64 v[222:223], s[24:25], 0, v[158:159]
	s_addc_u32 s85, s25, 0
	s_add_i32 s83, s97, s28
	global_load_lds_dwordx4 v[222:223], off
	v_lshl_add_u64 v[224:225], s[84:85], 0, v[154:155]
	s_mov_b32 m0, s83
	v_lshl_add_u64 v[226:227], s[26:27], 0, v[156:157]
	global_load_lds_dwordx4 v[224:225], off
	v_lshl_add_u64 v[224:225], s[84:85], 0, v[158:159]
	s_add_i32 m0, s83, 0x2000
	s_nop 0
	global_load_lds_dwordx4 v[224:225], off
	v_lshl_add_u64 v[224:225], s[26:27], 0, v[152:153]
	s_mov_b32 m0, s29
	s_nop 0
	global_load_lds_dwordx4 v[224:225], off
	s_mov_b32 m0, s30
	s_nop 0
	global_load_lds_dwordx4 v[226:227], off
	s_waitcnt vmcnt(8)
	s_waitcnt lgkmcnt(0)
	s_barrier
	s_setprio 1
	s_waitcnt lgkmcnt(0)
	v_mfma_f32_16x16x32_bf16 v[76:79], v[24:27], v[188:191], v[76:79]
	v_mfma_f32_16x16x32_bf16 v[72:75], v[44:47], v[188:191], v[72:75]
	v_mfma_f32_16x16x32_bf16 v[60:63], v[24:27], v[196:199], v[60:63]
	v_mfma_f32_16x16x32_bf16 v[56:59], v[44:47], v[196:199], v[56:59]
	v_mfma_f32_16x16x32_bf16 v[36:39], v[24:27], v[204:207], v[36:39]
	v_mfma_f32_16x16x32_bf16 v[32:35], v[44:47], v[204:207], v[32:35]
	v_mfma_f32_16x16x32_bf16 v[12:15], v[24:27], v[214:217], v[12:15]
	v_mfma_f32_16x16x32_bf16 v[8:11], v[44:47], v[214:217], v[8:11]
	v_mfma_f32_16x16x32_bf16 v[76:79], v[28:31], v[192:195], v[76:79]
	v_mfma_f32_16x16x32_bf16 v[72:75], v[52:55], v[192:195], v[72:75]
	v_mfma_f32_16x16x32_bf16 v[60:63], v[28:31], v[200:203], v[60:63]
	v_mfma_f32_16x16x32_bf16 v[56:59], v[52:55], v[200:203], v[56:59]
	v_mfma_f32_16x16x32_bf16 v[36:39], v[28:31], v[210:213], v[36:39]
	v_mfma_f32_16x16x32_bf16 v[32:35], v[52:55], v[210:213], v[32:35]
	v_mfma_f32_16x16x32_bf16 v[12:15], v[28:31], v[218:221], v[12:15]
	v_mfma_f32_16x16x32_bf16 v[8:11], v[52:55], v[218:221], v[8:11]
	s_setprio 0
	s_setprio 1
	v_mfma_f32_16x16x32_bf16 v[40:43], v[170:173], v[196:199], v[40:43]
	v_mfma_f32_16x16x32_bf16 v[20:23], v[144:147], v[204:207], v[20:23]
	v_mfma_f32_16x16x32_bf16 v[16:19], v[170:173], v[204:207], v[16:19]
	v_mfma_f32_16x16x32_bf16 v[4:7], v[144:147], v[214:217], v[4:7]
	v_mfma_f32_16x16x32_bf16 v[0:3], v[170:173], v[214:217], v[0:3]
	v_mfma_f32_16x16x32_bf16 v[24:27], v[144:147], v[188:191], v[68:71]
	v_mfma_f32_16x16x32_bf16 v[28:31], v[170:173], v[188:191], v[64:67]
	v_mfma_f32_16x16x32_bf16 v[44:47], v[144:147], v[196:199], v[48:51]
	v_mfma_f32_16x16x32_bf16 v[40:43], v[184:187], v[200:203], v[40:43]
	v_mfma_f32_16x16x32_bf16 v[20:23], v[148:151], v[210:213], v[20:23]
	v_mfma_f32_16x16x32_bf16 v[16:19], v[184:187], v[210:213], v[16:19]
	v_mfma_f32_16x16x32_bf16 v[4:7], v[148:151], v[218:221], v[4:7]
	v_mfma_f32_16x16x32_bf16 v[0:3], v[184:187], v[218:221], v[0:3]
	v_mfma_f32_16x16x32_bf16 v[24:27], v[148:151], v[192:195], v[24:27]
	v_mfma_f32_16x16x32_bf16 v[28:31], v[184:187], v[192:195], v[28:31]
	v_mfma_f32_16x16x32_bf16 v[44:47], v[148:151], v[200:203], v[44:47]
	s_setprio 0
	s_barrier
	s_add_i32 s83, 0, 0x18000
	s_add_i32 s84, 0, 0x1c000
	v_add_u32_e32 v68, s83, v177
	v_add_u32_e32 v160, s84, v177
	ds_read_b128 v[48:51], v68
	ds_read_b128 v[52:55], v68 offset:1024
	ds_read_b128 v[64:67], v68 offset:2048
	ds_read_b128 v[68:71], v68 offset:3072
	ds_read_b128 v[144:147], v160
	ds_read_b128 v[148:151], v160 offset:1024
	ds_read_b128 v[170:173], v160 offset:2048
	ds_read_b128 v[184:187], v160 offset:3072
	s_add_u32 s26, s26, 0x40000
	s_addc_u32 s27, s27, 0
	s_mov_b32 m0, s31
	v_lshl_add_u64 v[228:229], s[26:27], 0, v[152:153]
	ds_read_b128 v[188:191], v181 offset:32768
	ds_read_b128 v[192:195], v181 offset:33792
	ds_read_b128 v[196:199], v181 offset:34816
	ds_read_b128 v[200:203], v181 offset:35840
	ds_read_b128 v[204:207], v181 offset:36864
	ds_read_b128 v[210:213], v181 offset:37888
	ds_read_b128 v[214:217], v181 offset:38912
	ds_read_b128 v[218:221], v181 offset:39936
	global_load_lds_dwordx4 v[228:229], off
	v_lshl_add_u64 v[228:229], s[26:27], 0, v[156:157]
	s_mov_b32 m0, s34
	s_nop 0
	global_load_lds_dwordx4 v[228:229], off
	s_waitcnt vmcnt(8)
	s_waitcnt lgkmcnt(0)
	s_barrier
	s_setprio 1
	s_waitcnt lgkmcnt(0)
	v_mfma_f32_16x16x32_bf16 v[140:143], v[48:51], v[188:191], v[140:143]
	v_mfma_f32_16x16x32_bf16 v[136:139], v[64:67], v[188:191], v[136:139]
	v_mfma_f32_16x16x32_bf16 v[124:127], v[48:51], v[196:199], v[124:127]
	v_mfma_f32_16x16x32_bf16 v[120:123], v[64:67], v[196:199], v[120:123]
	v_mfma_f32_16x16x32_bf16 v[108:111], v[48:51], v[204:207], v[108:111]
	v_mfma_f32_16x16x32_bf16 v[104:107], v[64:67], v[204:207], v[104:107]
	v_mfma_f32_16x16x32_bf16 v[92:95], v[48:51], v[214:217], v[92:95]
	v_mfma_f32_16x16x32_bf16 v[88:91], v[64:67], v[214:217], v[88:91]
	v_mfma_f32_16x16x32_bf16 v[140:143], v[52:55], v[192:195], v[140:143]
	v_mfma_f32_16x16x32_bf16 v[136:139], v[68:71], v[192:195], v[136:139]
	v_mfma_f32_16x16x32_bf16 v[124:127], v[52:55], v[200:203], v[124:127]
	v_mfma_f32_16x16x32_bf16 v[120:123], v[68:71], v[200:203], v[120:123]
	v_mfma_f32_16x16x32_bf16 v[108:111], v[52:55], v[210:213], v[108:111]
	v_mfma_f32_16x16x32_bf16 v[104:107], v[68:71], v[210:213], v[104:107]
	v_mfma_f32_16x16x32_bf16 v[92:95], v[52:55], v[218:221], v[92:95]
	v_mfma_f32_16x16x32_bf16 v[88:91], v[68:71], v[218:221], v[88:91]
	s_setprio 0
	s_setprio 1
	v_mfma_f32_16x16x32_bf16 v[132:135], v[144:147], v[188:191], v[132:135]
	v_mfma_f32_16x16x32_bf16 v[128:131], v[170:173], v[188:191], v[128:131]
	v_mfma_f32_16x16x32_bf16 v[116:119], v[144:147], v[196:199], v[116:119]
	v_mfma_f32_16x16x32_bf16 v[112:115], v[170:173], v[196:199], v[112:115]
	v_mfma_f32_16x16x32_bf16 v[100:103], v[144:147], v[204:207], v[100:103]
	v_mfma_f32_16x16x32_bf16 v[96:99], v[170:173], v[204:207], v[96:99]
	v_mfma_f32_16x16x32_bf16 v[84:87], v[144:147], v[214:217], v[84:87]
	v_mfma_f32_16x16x32_bf16 v[80:83], v[170:173], v[214:217], v[80:83]
	v_mfma_f32_16x16x32_bf16 v[132:135], v[148:151], v[192:195], v[132:135]
	v_mfma_f32_16x16x32_bf16 v[128:131], v[184:187], v[192:195], v[128:131]
	v_mfma_f32_16x16x32_bf16 v[116:119], v[148:151], v[200:203], v[116:119]
	v_mfma_f32_16x16x32_bf16 v[112:115], v[184:187], v[200:203], v[112:115]
	v_mfma_f32_16x16x32_bf16 v[100:103], v[148:151], v[210:213], v[100:103]
	v_mfma_f32_16x16x32_bf16 v[96:99], v[184:187], v[210:213], v[96:99]
	v_mfma_f32_16x16x32_bf16 v[84:87], v[148:151], v[218:221], v[84:87]
	v_mfma_f32_16x16x32_bf16 v[80:83], v[184:187], v[218:221], v[80:83]
	s_setprio 0
	s_barrier
	s_add_i32 s26, s83, s28
	v_lshl_add_u64 v[174:175], v[174:175], 0, s[16:17]
	s_mov_b32 m0, s26
	ds_read_b128 v[188:191], v181 offset:49152
	ds_read_b128 v[192:195], v181 offset:50176
	ds_read_b128 v[196:199], v181 offset:51200
	ds_read_b128 v[200:203], v181 offset:52224
	ds_read_b128 v[204:207], v181 offset:53248
	ds_read_b128 v[210:213], v181 offset:54272
	ds_read_b128 v[214:217], v181 offset:55296
	ds_read_b128 v[218:221], v181 offset:56320
	global_load_lds_dwordx4 v[174:175], off
	s_add_i32 m0, s26, 0x2000
	s_add_u32 s24, s24, 0x40080
	v_lshl_add_u64 v[174:175], v[222:223], 0, s[16:17]
	s_addc_u32 s25, s25, 0
	s_add_i32 s26, s84, s28
	global_load_lds_dwordx4 v[174:175], off
	v_lshl_add_u64 v[174:175], s[24:25], 0, v[154:155]
	s_mov_b32 m0, s26
	s_nop 0
	global_load_lds_dwordx4 v[174:175], off
	v_lshl_add_u64 v[174:175], s[24:25], 0, v[158:159]
	s_add_i32 m0, s26, 0x2000
	s_nop 0
	global_load_lds_dwordx4 v[174:175], off
	v_lshl_add_u64 v[174:175], v[224:225], 0, s[16:17]
	s_mov_b32 m0, s36
	s_nop 0
	global_load_lds_dwordx4 v[174:175], off
	v_lshl_add_u64 v[174:175], v[226:227], 0, s[16:17]
	s_mov_b32 m0, s37
	s_nop 0
	global_load_lds_dwordx4 v[174:175], off
	s_waitcnt vmcnt(8)
	s_waitcnt lgkmcnt(0)
	s_barrier
	s_setprio 1
	s_waitcnt lgkmcnt(0)
	v_mfma_f32_16x16x32_bf16 v[76:79], v[48:51], v[188:191], v[76:79]
	v_mfma_f32_16x16x32_bf16 v[72:75], v[64:67], v[188:191], v[72:75]
	v_mfma_f32_16x16x32_bf16 v[60:63], v[48:51], v[196:199], v[60:63]
	v_mfma_f32_16x16x32_bf16 v[56:59], v[64:67], v[196:199], v[56:59]
	v_mfma_f32_16x16x32_bf16 v[36:39], v[48:51], v[204:207], v[36:39]
	v_mfma_f32_16x16x32_bf16 v[32:35], v[64:67], v[204:207], v[32:35]
	v_mfma_f32_16x16x32_bf16 v[12:15], v[48:51], v[214:217], v[12:15]
	v_mfma_f32_16x16x32_bf16 v[8:11], v[64:67], v[214:217], v[8:11]
	v_mfma_f32_16x16x32_bf16 v[76:79], v[52:55], v[192:195], v[76:79]
	v_mfma_f32_16x16x32_bf16 v[72:75], v[68:71], v[192:195], v[72:75]
	v_mfma_f32_16x16x32_bf16 v[60:63], v[52:55], v[200:203], v[60:63]
	v_mfma_f32_16x16x32_bf16 v[56:59], v[68:71], v[200:203], v[56:59]
	v_mfma_f32_16x16x32_bf16 v[36:39], v[52:55], v[210:213], v[36:39]
	v_mfma_f32_16x16x32_bf16 v[32:35], v[68:71], v[210:213], v[32:35]
	v_mfma_f32_16x16x32_bf16 v[12:15], v[52:55], v[218:221], v[12:15]
	v_mfma_f32_16x16x32_bf16 v[8:11], v[68:71], v[218:221], v[8:11]
	s_setprio 0
	s_setprio 1
	v_mfma_f32_16x16x32_bf16 v[24:27], v[144:147], v[188:191], v[24:27]
	v_mfma_f32_16x16x32_bf16 v[68:71], v[148:151], v[192:195], v[24:27]
	v_mfma_f32_16x16x32_bf16 v[24:27], v[170:173], v[188:191], v[28:31]
	v_mfma_f32_16x16x32_bf16 v[64:67], v[184:187], v[192:195], v[24:27]
	v_mfma_f32_16x16x32_bf16 v[24:27], v[144:147], v[196:199], v[44:47]
	v_mfma_f32_16x16x32_bf16 v[48:51], v[148:151], v[200:203], v[24:27]
	v_mfma_f32_16x16x32_bf16 v[24:27], v[170:173], v[196:199], v[40:43]
	v_mfma_f32_16x16x32_bf16 v[20:23], v[144:147], v[204:207], v[20:23]
	v_mfma_f32_16x16x32_bf16 v[16:19], v[170:173], v[204:207], v[16:19]
	v_mfma_f32_16x16x32_bf16 v[4:7], v[144:147], v[214:217], v[4:7]
	v_mfma_f32_16x16x32_bf16 v[0:3], v[170:173], v[214:217], v[0:3]
	v_mfma_f32_16x16x32_bf16 v[40:43], v[184:187], v[200:203], v[24:27]
	v_mfma_f32_16x16x32_bf16 v[20:23], v[148:151], v[210:213], v[20:23]
	v_mfma_f32_16x16x32_bf16 v[16:19], v[184:187], v[210:213], v[16:19]
	v_mfma_f32_16x16x32_bf16 v[4:7], v[148:151], v[218:221], v[4:7]
	v_mfma_f32_16x16x32_bf16 v[0:3], v[184:187], v[218:221], v[0:3]
	s_setprio 0
	s_add_i32 s82, s82, 2
	s_add_u32 s6, s6, 0x100
	s_addc_u32 s7, s7, 0
	s_add_u32 s9, s9, 0x100
	s_addc_u32 s21, s21, 0
	s_cmp_gt_u32 s82, 13
	s_barrier
	s_cbranch_scc0 .LBB0_143
	s_and_b64 vcc, exec, s[18:19]
	s_cbranch_vccz .LBB0_146
	s_barrier

.LBB0_577:
	ds_read_b128 v[166:169], v177
	ds_read_b128 v[170:173], v177 offset:1024
	ds_read_b128 v[180:183], v177 offset:2048
	ds_read_b128 v[184:187], v177 offset:3072
	ds_read_b128 v[188:191], v178
	ds_read_b128 v[192:195], v178 offset:1024
	ds_read_b128 v[196:199], v178 offset:2048
	ds_read_b128 v[200:203], v178 offset:3072
	s_add_i32 s67, s28, 2
	s_add_u32 s29, s26, 0xfffc0080
	s_addc_u32 s34, s27, -1
	s_cmp_eq_u32 s23, s28
	s_cselect_b32 s28, s24, s31
	s_cselect_b32 s35, s1, s34
	s_cselect_b32 s34, s0, s29
	s_cselect_b32 s29, s25, s66
	v_lshl_add_u64 v[174:175], s[26:27], 0, v[156:157]
	s_add_i32 m0, s37, 0xc000
	ds_read_b128 v[204:207], v179
	ds_read_b128 v[210:213], v179 offset:1024
	ds_read_b128 v[214:217], v179 offset:2048
	ds_read_b128 v[218:221], v179 offset:3072
	ds_read_b128 v[222:225], v179 offset:4096
	ds_read_b128 v[226:229], v179 offset:5120
	ds_read_b128 v[230:233], v179 offset:6144
	ds_read_b128 v[234:237], v179 offset:7168
	global_load_lds_dwordx4 v[174:175], off
	v_lshl_add_u64 v[174:175], s[26:27], 0, v[158:159]
	s_add_i32 m0, s37, 0xe000
	s_nop 0
	global_load_lds_dwordx4 v[174:175], off
	s_waitcnt vmcnt(8)
	s_waitcnt lgkmcnt(0)
	s_barrier
	s_setprio 1
	s_waitcnt lgkmcnt(0)
	v_mfma_f32_16x16x32_bf16 v[124:127], v[166:169], v[204:207], v[124:127]
	v_mfma_f32_16x16x32_bf16 v[120:123], v[180:183], v[204:207], v[120:123]
	v_mfma_f32_16x16x32_bf16 v[108:111], v[166:169], v[214:217], v[108:111]
	v_mfma_f32_16x16x32_bf16 v[104:107], v[180:183], v[214:217], v[104:107]
	v_mfma_f32_16x16x32_bf16 v[92:95], v[166:169], v[222:225], v[92:95]
	v_mfma_f32_16x16x32_bf16 v[88:91], v[180:183], v[222:225], v[88:91]
	v_mfma_f32_16x16x32_bf16 v[76:79], v[166:169], v[230:233], v[76:79]
	v_mfma_f32_16x16x32_bf16 v[72:75], v[180:183], v[230:233], v[72:75]
	v_mfma_f32_16x16x32_bf16 v[124:127], v[170:173], v[210:213], v[124:127]
	v_mfma_f32_16x16x32_bf16 v[120:123], v[184:187], v[210:213], v[120:123]
	v_mfma_f32_16x16x32_bf16 v[108:111], v[170:173], v[218:221], v[108:111]
	v_mfma_f32_16x16x32_bf16 v[104:107], v[184:187], v[218:221], v[104:107]
	v_mfma_f32_16x16x32_bf16 v[92:95], v[170:173], v[226:229], v[92:95]
	v_mfma_f32_16x16x32_bf16 v[88:91], v[184:187], v[226:229], v[88:91]
	v_mfma_f32_16x16x32_bf16 v[76:79], v[170:173], v[234:237], v[76:79]
	v_mfma_f32_16x16x32_bf16 v[72:75], v[184:187], v[234:237], v[72:75]
	s_setprio 0
	s_setprio 1
	v_mfma_f32_16x16x32_bf16 v[116:119], v[188:191], v[204:207], v[116:119]
	v_mfma_f32_16x16x32_bf16 v[112:115], v[196:199], v[204:207], v[112:115]
	v_mfma_f32_16x16x32_bf16 v[100:103], v[188:191], v[214:217], v[100:103]
	v_mfma_f32_16x16x32_bf16 v[96:99], v[196:199], v[214:217], v[96:99]
	v_mfma_f32_16x16x32_bf16 v[84:87], v[188:191], v[222:225], v[84:87]
	v_mfma_f32_16x16x32_bf16 v[80:83], v[196:199], v[222:225], v[80:83]
	v_mfma_f32_16x16x32_bf16 v[68:71], v[188:191], v[230:233], v[68:71]
	v_mfma_f32_16x16x32_bf16 v[64:67], v[196:199], v[230:233], v[64:67]
	v_mfma_f32_16x16x32_bf16 v[116:119], v[192:195], v[210:213], v[116:119]
	v_mfma_f32_16x16x32_bf16 v[112:115], v[200:203], v[210:213], v[112:115]
	v_mfma_f32_16x16x32_bf16 v[100:103], v[192:195], v[218:221], v[100:103]
	v_mfma_f32_16x16x32_bf16 v[96:99], v[200:203], v[218:221], v[96:99]
	v_mfma_f32_16x16x32_bf16 v[84:87], v[192:195], v[226:229], v[84:87]
	v_mfma_f32_16x16x32_bf16 v[80:83], v[200:203], v[226:229], v[80:83]
	v_mfma_f32_16x16x32_bf16 v[68:71], v[192:195], v[234:237], v[68:71]
	v_mfma_f32_16x16x32_bf16 v[64:67], v[200:203], v[234:237], v[64:67]
	s_setprio 0
	s_barrier
	s_add_i32 s68, s59, s36
	v_lshl_add_u64 v[174:175], s[28:29], 0, v[130:131]
	s_mov_b32 m0, s68
	ds_read_b128 v[204:207], v179 offset:16384
	ds_read_b128 v[210:213], v179 offset:17408
	ds_read_b128 v[214:217], v179 offset:18432
	ds_read_b128 v[218:221], v179 offset:19456
	ds_read_b128 v[222:225], v179 offset:20480
	ds_read_b128 v[226:229], v179 offset:21504
	ds_read_b128 v[230:233], v179 offset:22528
	ds_read_b128 v[234:237], v179 offset:23552
	global_load_lds_dwordx4 v[174:175], off
	s_add_i32 m0, s68, 0x2000
	s_add_u32 s68, s28, 0x40000
	v_lshl_add_u64 v[238:239], s[28:29], 0, v[134:135]
	s_addc_u32 s69, s29, 0
	s_add_i32 s70, s60, s36
	global_load_lds_dwordx4 v[238:239], off
	v_lshl_add_u64 v[240:241], s[68:69], 0, v[130:131]
	s_mov_b32 m0, s70
	v_lshl_add_u64 v[242:243], s[34:35], 0, v[132:133]
	global_load_lds_dwordx4 v[240:241], off
	v_lshl_add_u64 v[240:241], s[68:69], 0, v[134:135]
	s_add_i32 m0, s70, 0x2000
	s_nop 0
	global_load_lds_dwordx4 v[240:241], off
	v_lshl_add_u64 v[240:241], s[34:35], 0, v[128:129]
	s_mov_b32 m0, s37
	s_nop 0
	global_load_lds_dwordx4 v[240:241], off
	s_mov_b32 m0, s44
	s_nop 0
	global_load_lds_dwordx4 v[242:243], off
	s_waitcnt vmcnt(8)
	s_waitcnt lgkmcnt(0)
	s_barrier
	s_setprio 1
	s_waitcnt lgkmcnt(0)
	v_mfma_f32_16x16x32_bf16 v[60:63], v[166:169], v[204:207], v[60:63]
	v_mfma_f32_16x16x32_bf16 v[56:59], v[180:183], v[204:207], v[56:59]
	v_mfma_f32_16x16x32_bf16 v[44:47], v[166:169], v[214:217], v[44:47]
	v_mfma_f32_16x16x32_bf16 v[40:43], v[180:183], v[214:217], v[40:43]
	v_mfma_f32_16x16x32_bf16 v[28:31], v[166:169], v[222:225], v[28:31]
	v_mfma_f32_16x16x32_bf16 v[24:27], v[180:183], v[222:225], v[24:27]
	v_mfma_f32_16x16x32_bf16 v[12:15], v[166:169], v[230:233], v[12:15]
	v_mfma_f32_16x16x32_bf16 v[8:11], v[180:183], v[230:233], v[8:11]
	v_mfma_f32_16x16x32_bf16 v[60:63], v[170:173], v[210:213], v[60:63]
	v_mfma_f32_16x16x32_bf16 v[56:59], v[184:187], v[210:213], v[56:59]
	v_mfma_f32_16x16x32_bf16 v[44:47], v[170:173], v[218:221], v[44:47]
	v_mfma_f32_16x16x32_bf16 v[40:43], v[184:187], v[218:221], v[40:43]
	v_mfma_f32_16x16x32_bf16 v[28:31], v[170:173], v[226:229], v[28:31]
	v_mfma_f32_16x16x32_bf16 v[24:27], v[184:187], v[226:229], v[24:27]
	v_mfma_f32_16x16x32_bf16 v[12:15], v[170:173], v[234:237], v[12:15]
	v_mfma_f32_16x16x32_bf16 v[8:11], v[184:187], v[234:237], v[8:11]
	s_setprio 0
	s_setprio 1
	v_mfma_f32_16x16x32_bf16 v[52:55], v[188:191], v[204:207], v[52:55]
	v_mfma_f32_16x16x32_bf16 v[48:51], v[196:199], v[204:207], v[48:51]
	v_mfma_f32_16x16x32_bf16 v[36:39], v[188:191], v[214:217], v[36:39]
	v_mfma_f32_16x16x32_bf16 v[32:35], v[196:199], v[214:217], v[32:35]
	v_mfma_f32_16x16x32_bf16 v[20:23], v[188:191], v[222:225], v[20:23]
	v_mfma_f32_16x16x32_bf16 v[16:19], v[196:199], v[222:225], v[16:19]
	v_mfma_f32_16x16x32_bf16 v[4:7], v[188:191], v[230:233], v[4:7]
	v_mfma_f32_16x16x32_bf16 v[0:3], v[196:199], v[230:233], v[0:3]
	v_mfma_f32_16x16x32_bf16 v[52:55], v[192:195], v[210:213], v[52:55]
	v_mfma_f32_16x16x32_bf16 v[48:51], v[200:203], v[210:213], v[48:51]
	v_mfma_f32_16x16x32_bf16 v[36:39], v[192:195], v[218:221], v[36:39]
	v_mfma_f32_16x16x32_bf16 v[32:35], v[200:203], v[218:221], v[32:35]
	v_mfma_f32_16x16x32_bf16 v[20:23], v[192:195], v[226:229], v[20:23]
	v_mfma_f32_16x16x32_bf16 v[16:19], v[200:203], v[226:229], v[16:19]
	v_mfma_f32_16x16x32_bf16 v[4:7], v[192:195], v[234:237], v[4:7]
	v_mfma_f32_16x16x32_bf16 v[0:3], v[200:203], v[234:237], v[0:3]
	s_setprio 0
	s_barrier
	s_add_i32 s68, 0, 0x18000
	v_add_u32_e32 v136, s68, v176
	s_add_i32 s69, 0, 0x1c000
	ds_read_b128 v[166:169], v136
	ds_read_b128 v[170:173], v136 offset:1024
	ds_read_b128 v[180:183], v136 offset:2048
	ds_read_b128 v[184:187], v136 offset:3072
	v_add_u32_e32 v136, s69, v176
	ds_read_b128 v[188:191], v136
	ds_read_b128 v[192:195], v136 offset:1024
	ds_read_b128 v[196:199], v136 offset:2048
	ds_read_b128 v[200:203], v136 offset:3072
	s_add_u32 s34, s34, 0x40000
	s_addc_u32 s35, s35, 0
	s_mov_b32 m0, s45
	v_lshl_add_u64 v[244:245], s[34:35], 0, v[128:129]
	ds_read_b128 v[204:207], v179 offset:32768
	ds_read_b128 v[210:213], v179 offset:33792
	ds_read_b128 v[214:217], v179 offset:34816
	ds_read_b128 v[218:221], v179 offset:35840
	ds_read_b128 v[222:225], v179 offset:36864
	ds_read_b128 v[226:229], v179 offset:37888
	ds_read_b128 v[230:233], v179 offset:38912
	ds_read_b128 v[234:237], v179 offset:39936
	global_load_lds_dwordx4 v[244:245], off
	v_lshl_add_u64 v[244:245], s[34:35], 0, v[132:133]
	s_mov_b32 m0, s52
	s_nop 0
	global_load_lds_dwordx4 v[244:245], off
	s_waitcnt vmcnt(8)
	s_waitcnt lgkmcnt(0)
	s_barrier
	s_setprio 1
	s_waitcnt lgkmcnt(0)
	v_mfma_f32_16x16x32_bf16 v[124:127], v[166:169], v[204:207], v[124:127]
	v_mfma_f32_16x16x32_bf16 v[120:123], v[180:183], v[204:207], v[120:123]
	v_mfma_f32_16x16x32_bf16 v[108:111], v[166:169], v[214:217], v[108:111]
	v_mfma_f32_16x16x32_bf16 v[104:107], v[180:183], v[214:217], v[104:107]
	v_mfma_f32_16x16x32_bf16 v[92:95], v[166:169], v[222:225], v[92:95]
	v_mfma_f32_16x16x32_bf16 v[88:91], v[180:183], v[222:225], v[88:91]
	v_mfma_f32_16x16x32_bf16 v[76:79], v[166:169], v[230:233], v[76:79]
	v_mfma_f32_16x16x32_bf16 v[72:75], v[180:183], v[230:233], v[72:75]
	v_mfma_f32_16x16x32_bf16 v[124:127], v[170:173], v[210:213], v[124:127]
	v_mfma_f32_16x16x32_bf16 v[120:123], v[184:187], v[210:213], v[120:123]
	v_mfma_f32_16x16x32_bf16 v[108:111], v[170:173], v[218:221], v[108:111]
	v_mfma_f32_16x16x32_bf16 v[104:107], v[184:187], v[218:221], v[104:107]
	v_mfma_f32_16x16x32_bf16 v[92:95], v[170:173], v[226:229], v[92:95]
	v_mfma_f32_16x16x32_bf16 v[88:91], v[184:187], v[226:229], v[88:91]
	v_mfma_f32_16x16x32_bf16 v[76:79], v[170:173], v[234:237], v[76:79]
	v_mfma_f32_16x16x32_bf16 v[72:75], v[184:187], v[234:237], v[72:75]
	s_setprio 0
	s_setprio 1
	v_mfma_f32_16x16x32_bf16 v[116:119], v[188:191], v[204:207], v[116:119]
	v_mfma_f32_16x16x32_bf16 v[112:115], v[196:199], v[204:207], v[112:115]
	v_mfma_f32_16x16x32_bf16 v[100:103], v[188:191], v[214:217], v[100:103]
	v_mfma_f32_16x16x32_bf16 v[96:99], v[196:199], v[214:217], v[96:99]
	v_mfma_f32_16x16x32_bf16 v[84:87], v[188:191], v[222:225], v[84:87]
	v_mfma_f32_16x16x32_bf16 v[80:83], v[196:199], v[222:225], v[80:83]
	v_mfma_f32_16x16x32_bf16 v[68:71], v[188:191], v[230:233], v[68:71]
	v_mfma_f32_16x16x32_bf16 v[64:67], v[196:199], v[230:233], v[64:67]
	v_mfma_f32_16x16x32_bf16 v[116:119], v[192:195], v[210:213], v[116:119]
	v_mfma_f32_16x16x32_bf16 v[112:115], v[200:203], v[210:213], v[112:115]
	v_mfma_f32_16x16x32_bf16 v[100:103], v[192:195], v[218:221], v[100:103]
	v_mfma_f32_16x16x32_bf16 v[96:99], v[200:203], v[218:221], v[96:99]
	v_mfma_f32_16x16x32_bf16 v[84:87], v[192:195], v[226:229], v[84:87]
	v_mfma_f32_16x16x32_bf16 v[80:83], v[200:203], v[226:229], v[80:83]
	v_mfma_f32_16x16x32_bf16 v[68:71], v[192:195], v[234:237], v[68:71]
	v_mfma_f32_16x16x32_bf16 v[64:67], v[200:203], v[234:237], v[64:67]
	s_setprio 0
	s_barrier
	s_add_i32 s34, s68, s36
	v_lshl_add_u64 v[174:175], v[174:175], 0, s[16:17]
	s_mov_b32 m0, s34
	ds_read_b128 v[204:207], v179 offset:49152
	ds_read_b128 v[210:213], v179 offset:50176
	ds_read_b128 v[214:217], v179 offset:51200
	ds_read_b128 v[218:221], v179 offset:52224
	ds_read_b128 v[222:225], v179 offset:53248
	ds_read_b128 v[226:229], v179 offset:54272
	ds_read_b128 v[230:233], v179 offset:55296
	ds_read_b128 v[234:237], v179 offset:56320
	global_load_lds_dwordx4 v[174:175], off
	s_add_i32 m0, s34, 0x2000
	s_add_u32 s28, s28, 0x40080
	v_lshl_add_u64 v[174:175], v[238:239], 0, s[16:17]
	s_addc_u32 s29, s29, 0
	s_add_i32 s34, s69, s36
	global_load_lds_dwordx4 v[174:175], off
	v_lshl_add_u64 v[174:175], s[28:29], 0, v[130:131]
	s_mov_b32 m0, s34
	s_nop 0
	global_load_lds_dwordx4 v[174:175], off
	v_lshl_add_u64 v[174:175], s[28:29], 0, v[134:135]
	s_add_i32 m0, s34, 0x2000
	s_nop 0
	global_load_lds_dwordx4 v[174:175], off
	v_lshl_add_u64 v[174:175], v[240:241], 0, s[16:17]
	s_mov_b32 m0, s54
	s_nop 0
	global_load_lds_dwordx4 v[174:175], off
	v_lshl_add_u64 v[174:175], v[242:243], 0, s[16:17]
	s_mov_b32 m0, s55
	s_nop 0
	global_load_lds_dwordx4 v[174:175], off
	s_waitcnt vmcnt(8)
	s_waitcnt lgkmcnt(0)
	s_barrier
	s_setprio 1
	s_waitcnt lgkmcnt(0)
	v_mfma_f32_16x16x32_bf16 v[60:63], v[166:169], v[204:207], v[60:63]
	v_mfma_f32_16x16x32_bf16 v[56:59], v[180:183], v[204:207], v[56:59]
	v_mfma_f32_16x16x32_bf16 v[44:47], v[166:169], v[214:217], v[44:47]
	v_mfma_f32_16x16x32_bf16 v[40:43], v[180:183], v[214:217], v[40:43]
	v_mfma_f32_16x16x32_bf16 v[28:31], v[166:169], v[222:225], v[28:31]
	v_mfma_f32_16x16x32_bf16 v[24:27], v[180:183], v[222:225], v[24:27]
	v_mfma_f32_16x16x32_bf16 v[12:15], v[166:169], v[230:233], v[12:15]
	v_mfma_f32_16x16x32_bf16 v[8:11], v[180:183], v[230:233], v[8:11]
	v_mfma_f32_16x16x32_bf16 v[60:63], v[170:173], v[210:213], v[60:63]
	v_mfma_f32_16x16x32_bf16 v[56:59], v[184:187], v[210:213], v[56:59]
	v_mfma_f32_16x16x32_bf16 v[44:47], v[170:173], v[218:221], v[44:47]
	v_mfma_f32_16x16x32_bf16 v[40:43], v[184:187], v[218:221], v[40:43]
	v_mfma_f32_16x16x32_bf16 v[28:31], v[170:173], v[226:229], v[28:31]
	v_mfma_f32_16x16x32_bf16 v[24:27], v[184:187], v[226:229], v[24:27]
	v_mfma_f32_16x16x32_bf16 v[12:15], v[170:173], v[234:237], v[12:15]
	v_mfma_f32_16x16x32_bf16 v[8:11], v[184:187], v[234:237], v[8:11]
	s_setprio 0
	s_setprio 1
	v_mfma_f32_16x16x32_bf16 v[52:55], v[188:191], v[204:207], v[52:55]
	v_mfma_f32_16x16x32_bf16 v[48:51], v[196:199], v[204:207], v[48:51]
	v_mfma_f32_16x16x32_bf16 v[36:39], v[188:191], v[214:217], v[36:39]
	v_mfma_f32_16x16x32_bf16 v[32:35], v[196:199], v[214:217], v[32:35]
	v_mfma_f32_16x16x32_bf16 v[20:23], v[188:191], v[222:225], v[20:23]
	v_mfma_f32_16x16x32_bf16 v[16:19], v[196:199], v[222:225], v[16:19]
	v_mfma_f32_16x16x32_bf16 v[4:7], v[188:191], v[230:233], v[4:7]
	v_mfma_f32_16x16x32_bf16 v[0:3], v[196:199], v[230:233], v[0:3]
	v_mfma_f32_16x16x32_bf16 v[52:55], v[192:195], v[210:213], v[52:55]
	v_mfma_f32_16x16x32_bf16 v[48:51], v[200:203], v[210:213], v[48:51]
	v_mfma_f32_16x16x32_bf16 v[36:39], v[192:195], v[218:221], v[36:39]
	v_mfma_f32_16x16x32_bf16 v[32:35], v[200:203], v[218:221], v[32:35]
	v_mfma_f32_16x16x32_bf16 v[20:23], v[192:195], v[226:229], v[20:23]
	v_mfma_f32_16x16x32_bf16 v[16:19], v[200:203], v[226:229], v[16:19]
	v_mfma_f32_16x16x32_bf16 v[4:7], v[192:195], v[234:237], v[4:7]
	v_mfma_f32_16x16x32_bf16 v[0:3], v[200:203], v[234:237], v[0:3]
	s_setprio 0
	s_add_u32 s26, s26, 0x100
	s_addc_u32 s27, s27, 0
	s_add_u32 s31, s31, 0x100
	s_addc_u32 s66, s66, 0
	s_cmp_ge_u32 s67, s9
	s_mov_b32 s28, s67
	s_barrier
	s_cbranch_scc0 .LBB0_577
	s_and_b64 vcc, exec, s[18:19]
	s_cbranch_vccz .LBB0_580
	s_barrier

.LBB0_779:
	ds_read_b128 v[154:157], v151
	ds_read_b128 v[158:161], v151 offset:1024
	ds_read_b128 v[162:165], v151 offset:2048
	ds_read_b128 v[166:169], v151 offset:3072
	ds_read_b128 v[170:173], v152
	ds_read_b128 v[174:177], v152 offset:1024
	ds_read_b128 v[178:181], v152 offset:2048
	ds_read_b128 v[182:185], v152 offset:3072
	s_add_u32 s34, s28, 0xfffc0080
	s_addc_u32 s35, s29, -1
	s_cmp_eq_u32 s70, 12
	s_cselect_b32 s37, s1, s35
	s_cselect_b32 s36, s0, s34
	s_cselect_b32 s35, s25, s69
	s_cselect_b32 s34, s24, s23
	v_lshl_add_u64 v[146:147], s[28:29], 0, v[138:139]
	s_add_i32 m0, s27, 0xc000
	ds_read_b128 v[186:189], v153
	ds_read_b128 v[190:193], v153 offset:1024
	ds_read_b128 v[194:197], v153 offset:2048
	ds_read_b128 v[198:201], v153 offset:3072
	ds_read_b128 v[202:205], v153 offset:4096
	ds_read_b128 v[210:213], v153 offset:5120
	ds_read_b128 v[214:217], v153 offset:6144
	ds_read_b128 v[218:221], v153 offset:7168
	global_load_lds_dwordx4 v[146:147], off
	v_lshl_add_u64 v[146:147], s[28:29], 0, v[140:141]
	s_add_i32 m0, s27, 0xe000
	s_nop 0
	global_load_lds_dwordx4 v[146:147], off
	s_waitcnt vmcnt(8)
	s_waitcnt lgkmcnt(0)
	s_barrier
	s_setprio 1
	s_waitcnt lgkmcnt(0)
	v_mfma_f32_16x16x32_bf16 v[124:127], v[154:157], v[186:189], v[124:127]
	v_mfma_f32_16x16x32_bf16 v[120:123], v[162:165], v[186:189], v[120:123]
	v_mfma_f32_16x16x32_bf16 v[108:111], v[154:157], v[194:197], v[108:111]
	v_mfma_f32_16x16x32_bf16 v[104:107], v[162:165], v[194:197], v[104:107]
	v_mfma_f32_16x16x32_bf16 v[92:95], v[154:157], v[202:205], v[92:95]
	v_mfma_f32_16x16x32_bf16 v[88:91], v[162:165], v[202:205], v[88:91]
	v_mfma_f32_16x16x32_bf16 v[76:79], v[154:157], v[214:217], v[76:79]
	v_mfma_f32_16x16x32_bf16 v[72:75], v[162:165], v[214:217], v[72:75]
	v_mfma_f32_16x16x32_bf16 v[124:127], v[158:161], v[190:193], v[124:127]
	v_mfma_f32_16x16x32_bf16 v[120:123], v[166:169], v[190:193], v[120:123]
	v_mfma_f32_16x16x32_bf16 v[108:111], v[158:161], v[198:201], v[108:111]
	v_mfma_f32_16x16x32_bf16 v[104:107], v[166:169], v[198:201], v[104:107]
	v_mfma_f32_16x16x32_bf16 v[92:95], v[158:161], v[210:213], v[92:95]
	v_mfma_f32_16x16x32_bf16 v[88:91], v[166:169], v[210:213], v[88:91]
	v_mfma_f32_16x16x32_bf16 v[76:79], v[158:161], v[218:221], v[76:79]
	v_mfma_f32_16x16x32_bf16 v[72:75], v[166:169], v[218:221], v[72:75]
	s_setprio 0
	s_setprio 1
	v_mfma_f32_16x16x32_bf16 v[116:119], v[170:173], v[186:189], v[116:119]
	v_mfma_f32_16x16x32_bf16 v[112:115], v[178:181], v[186:189], v[112:115]
	v_mfma_f32_16x16x32_bf16 v[100:103], v[170:173], v[194:197], v[100:103]
	v_mfma_f32_16x16x32_bf16 v[96:99], v[178:181], v[194:197], v[96:99]
	v_mfma_f32_16x16x32_bf16 v[84:87], v[170:173], v[202:205], v[84:87]
	v_mfma_f32_16x16x32_bf16 v[80:83], v[178:181], v[202:205], v[80:83]
	v_mfma_f32_16x16x32_bf16 v[68:71], v[170:173], v[214:217], v[68:71]
	v_mfma_f32_16x16x32_bf16 v[64:67], v[178:181], v[214:217], v[64:67]
	v_mfma_f32_16x16x32_bf16 v[116:119], v[174:177], v[190:193], v[116:119]
	v_mfma_f32_16x16x32_bf16 v[112:115], v[182:185], v[190:193], v[112:115]
	v_mfma_f32_16x16x32_bf16 v[100:103], v[174:177], v[198:201], v[100:103]
	v_mfma_f32_16x16x32_bf16 v[96:99], v[182:185], v[198:201], v[96:99]
	v_mfma_f32_16x16x32_bf16 v[84:87], v[174:177], v[210:213], v[84:87]
	v_mfma_f32_16x16x32_bf16 v[80:83], v[182:185], v[210:213], v[80:83]
	v_mfma_f32_16x16x32_bf16 v[68:71], v[174:177], v[218:221], v[68:71]
	v_mfma_f32_16x16x32_bf16 v[64:67], v[182:185], v[218:221], v[64:67]
	s_setprio 0
	s_barrier
	s_add_i32 s71, s59, s30
	v_lshl_add_u64 v[146:147], s[34:35], 0, v[132:133]
	s_mov_b32 m0, s71
	ds_read_b128 v[186:189], v153 offset:16384
	ds_read_b128 v[190:193], v153 offset:17408
	ds_read_b128 v[194:197], v153 offset:18432
	ds_read_b128 v[198:201], v153 offset:19456
	ds_read_b128 v[202:205], v153 offset:20480
	ds_read_b128 v[210:213], v153 offset:21504
	ds_read_b128 v[214:217], v153 offset:22528
	ds_read_b128 v[218:221], v153 offset:23552
	global_load_lds_dwordx4 v[146:147], off
	s_add_i32 m0, s71, 0x2000
	s_add_u32 s80, s34, 0x40000
	v_lshl_add_u64 v[206:207], s[34:35], 0, v[128:129]
	s_addc_u32 s81, s35, 0
	s_add_i32 s71, s60, s30
	global_load_lds_dwordx4 v[206:207], off
	v_lshl_add_u64 v[222:223], s[80:81], 0, v[132:133]
	s_mov_b32 m0, s71
	v_lshl_add_u64 v[224:225], s[36:37], 0, v[130:131]
	global_load_lds_dwordx4 v[222:223], off
	v_lshl_add_u64 v[222:223], s[80:81], 0, v[128:129]
	s_add_i32 m0, s71, 0x2000
	s_nop 0
	global_load_lds_dwordx4 v[222:223], off
	v_lshl_add_u64 v[222:223], s[36:37], 0, v[134:135]
	s_mov_b32 m0, s27
	s_nop 0
	global_load_lds_dwordx4 v[222:223], off
	s_mov_b32 m0, s45
	s_nop 0
	global_load_lds_dwordx4 v[224:225], off
	s_waitcnt vmcnt(8)
	s_waitcnt lgkmcnt(0)
	s_barrier
	s_setprio 1
	s_waitcnt lgkmcnt(0)
	v_mfma_f32_16x16x32_bf16 v[60:63], v[154:157], v[186:189], v[60:63]
	v_mfma_f32_16x16x32_bf16 v[56:59], v[162:165], v[186:189], v[56:59]
	v_mfma_f32_16x16x32_bf16 v[44:47], v[154:157], v[194:197], v[44:47]
	v_mfma_f32_16x16x32_bf16 v[40:43], v[162:165], v[194:197], v[40:43]
	v_mfma_f32_16x16x32_bf16 v[28:31], v[154:157], v[202:205], v[28:31]
	v_mfma_f32_16x16x32_bf16 v[24:27], v[162:165], v[202:205], v[24:27]
	v_mfma_f32_16x16x32_bf16 v[12:15], v[154:157], v[214:217], v[12:15]
	v_mfma_f32_16x16x32_bf16 v[8:11], v[162:165], v[214:217], v[8:11]
	v_mfma_f32_16x16x32_bf16 v[60:63], v[158:161], v[190:193], v[60:63]
	v_mfma_f32_16x16x32_bf16 v[56:59], v[166:169], v[190:193], v[56:59]
	v_mfma_f32_16x16x32_bf16 v[44:47], v[158:161], v[198:201], v[44:47]
	v_mfma_f32_16x16x32_bf16 v[40:43], v[166:169], v[198:201], v[40:43]
	v_mfma_f32_16x16x32_bf16 v[28:31], v[158:161], v[210:213], v[28:31]
	v_mfma_f32_16x16x32_bf16 v[24:27], v[166:169], v[210:213], v[24:27]
	v_mfma_f32_16x16x32_bf16 v[12:15], v[158:161], v[218:221], v[12:15]
	v_mfma_f32_16x16x32_bf16 v[8:11], v[166:169], v[218:221], v[8:11]
	s_setprio 0
	s_setprio 1
	v_mfma_f32_16x16x32_bf16 v[52:55], v[170:173], v[186:189], v[52:55]
	v_mfma_f32_16x16x32_bf16 v[48:51], v[178:181], v[186:189], v[48:51]
	v_mfma_f32_16x16x32_bf16 v[36:39], v[170:173], v[194:197], v[36:39]
	v_mfma_f32_16x16x32_bf16 v[32:35], v[178:181], v[194:197], v[32:35]
	v_mfma_f32_16x16x32_bf16 v[20:23], v[170:173], v[202:205], v[20:23]
	v_mfma_f32_16x16x32_bf16 v[16:19], v[178:181], v[202:205], v[16:19]
	v_mfma_f32_16x16x32_bf16 v[4:7], v[170:173], v[214:217], v[4:7]
	v_mfma_f32_16x16x32_bf16 v[0:3], v[178:181], v[214:217], v[0:3]
	v_mfma_f32_16x16x32_bf16 v[52:55], v[174:177], v[190:193], v[52:55]
	v_mfma_f32_16x16x32_bf16 v[48:51], v[182:185], v[190:193], v[48:51]
	v_mfma_f32_16x16x32_bf16 v[36:39], v[174:177], v[198:201], v[36:39]
	v_mfma_f32_16x16x32_bf16 v[32:35], v[182:185], v[198:201], v[32:35]
	v_mfma_f32_16x16x32_bf16 v[20:23], v[174:177], v[210:213], v[20:23]
	v_mfma_f32_16x16x32_bf16 v[16:19], v[182:185], v[210:213], v[16:19]
	v_mfma_f32_16x16x32_bf16 v[4:7], v[174:177], v[218:221], v[4:7]
	v_mfma_f32_16x16x32_bf16 v[0:3], v[182:185], v[218:221], v[0:3]
	s_setprio 0
	s_barrier
	s_add_i32 s71, 0, 0x18000
	v_add_u32_e32 v136, s71, v149
	s_add_i32 s77, 0, 0x1c000
	ds_read_b128 v[154:157], v136
	ds_read_b128 v[158:161], v136 offset:1024
	ds_read_b128 v[162:165], v136 offset:2048
	ds_read_b128 v[166:169], v136 offset:3072
	v_add_u32_e32 v136, s77, v149
	ds_read_b128 v[170:173], v136
	ds_read_b128 v[174:177], v136 offset:1024
	ds_read_b128 v[178:181], v136 offset:2048
	ds_read_b128 v[182:185], v136 offset:3072
	s_add_u32 s36, s36, 0x40000
	s_addc_u32 s37, s37, 0
	s_mov_b32 m0, s52
	v_lshl_add_u64 v[226:227], s[36:37], 0, v[134:135]
	ds_read_b128 v[186:189], v153 offset:32768
	ds_read_b128 v[190:193], v153 offset:33792
	ds_read_b128 v[194:197], v153 offset:34816
	ds_read_b128 v[198:201], v153 offset:35840
	ds_read_b128 v[202:205], v153 offset:36864
	ds_read_b128 v[210:213], v153 offset:37888
	ds_read_b128 v[214:217], v153 offset:38912
	ds_read_b128 v[218:221], v153 offset:39936
	global_load_lds_dwordx4 v[226:227], off
	v_lshl_add_u64 v[226:227], s[36:37], 0, v[130:131]
	s_mov_b32 m0, s53
	s_nop 0
	global_load_lds_dwordx4 v[226:227], off
	s_waitcnt vmcnt(8)
	s_waitcnt lgkmcnt(0)
	s_barrier
	s_setprio 1
	s_waitcnt lgkmcnt(0)
	v_mfma_f32_16x16x32_bf16 v[124:127], v[154:157], v[186:189], v[124:127]
	v_mfma_f32_16x16x32_bf16 v[120:123], v[162:165], v[186:189], v[120:123]
	v_mfma_f32_16x16x32_bf16 v[108:111], v[154:157], v[194:197], v[108:111]
	v_mfma_f32_16x16x32_bf16 v[104:107], v[162:165], v[194:197], v[104:107]
	v_mfma_f32_16x16x32_bf16 v[92:95], v[154:157], v[202:205], v[92:95]
	v_mfma_f32_16x16x32_bf16 v[88:91], v[162:165], v[202:205], v[88:91]
	v_mfma_f32_16x16x32_bf16 v[76:79], v[154:157], v[214:217], v[76:79]
	v_mfma_f32_16x16x32_bf16 v[72:75], v[162:165], v[214:217], v[72:75]
	v_mfma_f32_16x16x32_bf16 v[124:127], v[158:161], v[190:193], v[124:127]
	v_mfma_f32_16x16x32_bf16 v[120:123], v[166:169], v[190:193], v[120:123]
	v_mfma_f32_16x16x32_bf16 v[108:111], v[158:161], v[198:201], v[108:111]
	v_mfma_f32_16x16x32_bf16 v[104:107], v[166:169], v[198:201], v[104:107]
	v_mfma_f32_16x16x32_bf16 v[92:95], v[158:161], v[210:213], v[92:95]
	v_mfma_f32_16x16x32_bf16 v[88:91], v[166:169], v[210:213], v[88:91]
	v_mfma_f32_16x16x32_bf16 v[76:79], v[158:161], v[218:221], v[76:79]
	v_mfma_f32_16x16x32_bf16 v[72:75], v[166:169], v[218:221], v[72:75]
	s_setprio 0
	s_setprio 1
	v_mfma_f32_16x16x32_bf16 v[116:119], v[170:173], v[186:189], v[116:119]
	v_mfma_f32_16x16x32_bf16 v[112:115], v[178:181], v[186:189], v[112:115]
	v_mfma_f32_16x16x32_bf16 v[100:103], v[170:173], v[194:197], v[100:103]
	v_mfma_f32_16x16x32_bf16 v[96:99], v[178:181], v[194:197], v[96:99]
	v_mfma_f32_16x16x32_bf16 v[84:87], v[170:173], v[202:205], v[84:87]
	v_mfma_f32_16x16x32_bf16 v[80:83], v[178:181], v[202:205], v[80:83]
	v_mfma_f32_16x16x32_bf16 v[68:71], v[170:173], v[214:217], v[68:71]
	v_mfma_f32_16x16x32_bf16 v[64:67], v[178:181], v[214:217], v[64:67]
	v_mfma_f32_16x16x32_bf16 v[116:119], v[174:177], v[190:193], v[116:119]
	v_mfma_f32_16x16x32_bf16 v[112:115], v[182:185], v[190:193], v[112:115]
	v_mfma_f32_16x16x32_bf16 v[100:103], v[174:177], v[198:201], v[100:103]
	v_mfma_f32_16x16x32_bf16 v[96:99], v[182:185], v[198:201], v[96:99]
	v_mfma_f32_16x16x32_bf16 v[84:87], v[174:177], v[210:213], v[84:87]
	v_mfma_f32_16x16x32_bf16 v[80:83], v[182:185], v[210:213], v[80:83]
	v_mfma_f32_16x16x32_bf16 v[68:71], v[174:177], v[218:221], v[68:71]
	v_mfma_f32_16x16x32_bf16 v[64:67], v[182:185], v[218:221], v[64:67]
	s_setprio 0
	s_barrier
	s_add_i32 s36, s71, s30
	v_lshl_add_u64 v[146:147], v[146:147], 0, s[14:15]
	s_mov_b32 m0, s36
	ds_read_b128 v[186:189], v153 offset:49152
	ds_read_b128 v[190:193], v153 offset:50176
	ds_read_b128 v[194:197], v153 offset:51200
	ds_read_b128 v[198:201], v153 offset:52224
	ds_read_b128 v[202:205], v153 offset:53248
	ds_read_b128 v[210:213], v153 offset:54272
	ds_read_b128 v[214:217], v153 offset:55296
	ds_read_b128 v[218:221], v153 offset:56320
	global_load_lds_dwordx4 v[146:147], off
	s_add_i32 m0, s36, 0x2000
	s_add_u32 s34, s34, 0x40080
	v_lshl_add_u64 v[146:147], v[206:207], 0, s[14:15]
	s_addc_u32 s35, s35, 0
	s_add_i32 s36, s77, s30
	global_load_lds_dwordx4 v[146:147], off
	v_lshl_add_u64 v[146:147], s[34:35], 0, v[132:133]
	s_mov_b32 m0, s36
	s_nop 0
	global_load_lds_dwordx4 v[146:147], off
	v_lshl_add_u64 v[146:147], s[34:35], 0, v[128:129]
	s_add_i32 m0, s36, 0x2000
	s_nop 0
	global_load_lds_dwordx4 v[146:147], off
	v_lshl_add_u64 v[146:147], v[222:223], 0, s[14:15]
	s_mov_b32 m0, s55
	s_nop 0
	global_load_lds_dwordx4 v[146:147], off
	v_lshl_add_u64 v[146:147], v[224:225], 0, s[14:15]
	s_mov_b32 m0, s56
	s_nop 0
	global_load_lds_dwordx4 v[146:147], off
	s_waitcnt vmcnt(8)
	s_waitcnt lgkmcnt(0)
	s_barrier
	s_setprio 1
	s_waitcnt lgkmcnt(0)
	v_mfma_f32_16x16x32_bf16 v[60:63], v[154:157], v[186:189], v[60:63]
	v_mfma_f32_16x16x32_bf16 v[56:59], v[162:165], v[186:189], v[56:59]
	v_mfma_f32_16x16x32_bf16 v[44:47], v[154:157], v[194:197], v[44:47]
	v_mfma_f32_16x16x32_bf16 v[40:43], v[162:165], v[194:197], v[40:43]
	v_mfma_f32_16x16x32_bf16 v[28:31], v[154:157], v[202:205], v[28:31]
	v_mfma_f32_16x16x32_bf16 v[24:27], v[162:165], v[202:205], v[24:27]
	v_mfma_f32_16x16x32_bf16 v[12:15], v[154:157], v[214:217], v[12:15]
	v_mfma_f32_16x16x32_bf16 v[8:11], v[162:165], v[214:217], v[8:11]
	v_mfma_f32_16x16x32_bf16 v[60:63], v[158:161], v[190:193], v[60:63]
	v_mfma_f32_16x16x32_bf16 v[56:59], v[166:169], v[190:193], v[56:59]
	v_mfma_f32_16x16x32_bf16 v[44:47], v[158:161], v[198:201], v[44:47]
	v_mfma_f32_16x16x32_bf16 v[40:43], v[166:169], v[198:201], v[40:43]
	v_mfma_f32_16x16x32_bf16 v[28:31], v[158:161], v[210:213], v[28:31]
	v_mfma_f32_16x16x32_bf16 v[24:27], v[166:169], v[210:213], v[24:27]
	v_mfma_f32_16x16x32_bf16 v[12:15], v[158:161], v[218:221], v[12:15]
	v_mfma_f32_16x16x32_bf16 v[8:11], v[166:169], v[218:221], v[8:11]
	s_setprio 0
	s_setprio 1
	v_mfma_f32_16x16x32_bf16 v[52:55], v[170:173], v[186:189], v[52:55]
	v_mfma_f32_16x16x32_bf16 v[48:51], v[178:181], v[186:189], v[48:51]
	v_mfma_f32_16x16x32_bf16 v[36:39], v[170:173], v[194:197], v[36:39]
	v_mfma_f32_16x16x32_bf16 v[32:35], v[178:181], v[194:197], v[32:35]
	v_mfma_f32_16x16x32_bf16 v[20:23], v[170:173], v[202:205], v[20:23]
	v_mfma_f32_16x16x32_bf16 v[16:19], v[178:181], v[202:205], v[16:19]
	v_mfma_f32_16x16x32_bf16 v[4:7], v[170:173], v[214:217], v[4:7]
	v_mfma_f32_16x16x32_bf16 v[0:3], v[178:181], v[214:217], v[0:3]
	v_mfma_f32_16x16x32_bf16 v[52:55], v[174:177], v[190:193], v[52:55]
	v_mfma_f32_16x16x32_bf16 v[48:51], v[182:185], v[190:193], v[48:51]
	v_mfma_f32_16x16x32_bf16 v[36:39], v[174:177], v[198:201], v[36:39]
	v_mfma_f32_16x16x32_bf16 v[32:35], v[182:185], v[198:201], v[32:35]
	v_mfma_f32_16x16x32_bf16 v[20:23], v[174:177], v[210:213], v[20:23]
	v_mfma_f32_16x16x32_bf16 v[16:19], v[182:185], v[210:213], v[16:19]
	v_mfma_f32_16x16x32_bf16 v[4:7], v[174:177], v[218:221], v[4:7]
	v_mfma_f32_16x16x32_bf16 v[0:3], v[182:185], v[218:221], v[0:3]
	s_setprio 0
	s_add_i32 s70, s70, 2
	s_add_u32 s28, s28, 0x100
	s_addc_u32 s29, s29, 0
	s_add_u32 s23, s23, 0x100
	s_addc_u32 s69, s69, 0
	s_cmp_gt_u32 s70, 13
	s_barrier
	s_cbranch_scc0 .LBB0_779
	s_and_b64 vcc, exec, s[16:17]
	s_cbranch_vccz .LBB0_782
	s_barrier

.LBB0_875:
	ds_read_b128 v[166:169], v177
	ds_read_b128 v[170:173], v177 offset:1024
	ds_read_b128 v[180:183], v177 offset:2048
	ds_read_b128 v[184:187], v177 offset:3072
	ds_read_b128 v[188:191], v178
	ds_read_b128 v[192:195], v178 offset:1024
	ds_read_b128 v[196:199], v178 offset:2048
	ds_read_b128 v[200:203], v178 offset:3072
	s_add_i32 s71, s36, 2
	s_add_u32 s37, s34, 0xfff00080
	s_addc_u32 s44, s35, -1
	s_cmp_eq_u32 s27, s36
	s_cselect_b32 s36, s28, s30
	s_cselect_b32 s45, s1, s44
	s_cselect_b32 s44, s0, s37
	s_cselect_b32 s37, s29, s31
	v_lshl_add_u64 v[174:175], s[34:35], 0, v[156:157]
	s_add_i32 m0, s53, 0xc000
	ds_read_b128 v[204:207], v179
	ds_read_b128 v[210:213], v179 offset:1024
	ds_read_b128 v[214:217], v179 offset:2048
	ds_read_b128 v[218:221], v179 offset:3072
	ds_read_b128 v[222:225], v179 offset:4096
	ds_read_b128 v[226:229], v179 offset:5120
	ds_read_b128 v[230:233], v179 offset:6144
	ds_read_b128 v[234:237], v179 offset:7168
	global_load_lds_dwordx4 v[174:175], off
	v_lshl_add_u64 v[174:175], s[34:35], 0, v[158:159]
	s_add_i32 m0, s53, 0xe000
	s_nop 0
	global_load_lds_dwordx4 v[174:175], off
	s_waitcnt vmcnt(8)
	s_waitcnt lgkmcnt(0)
	s_barrier
	s_setprio 1
	s_waitcnt lgkmcnt(0)
	v_mfma_f32_16x16x32_bf16 v[124:127], v[166:169], v[204:207], v[124:127]
	v_mfma_f32_16x16x32_bf16 v[120:123], v[180:183], v[204:207], v[120:123]
	v_mfma_f32_16x16x32_bf16 v[108:111], v[166:169], v[214:217], v[108:111]
	v_mfma_f32_16x16x32_bf16 v[104:107], v[180:183], v[214:217], v[104:107]
	v_mfma_f32_16x16x32_bf16 v[92:95], v[166:169], v[222:225], v[92:95]
	v_mfma_f32_16x16x32_bf16 v[88:91], v[180:183], v[222:225], v[88:91]
	v_mfma_f32_16x16x32_bf16 v[76:79], v[166:169], v[230:233], v[76:79]
	v_mfma_f32_16x16x32_bf16 v[72:75], v[180:183], v[230:233], v[72:75]
	v_mfma_f32_16x16x32_bf16 v[124:127], v[170:173], v[210:213], v[124:127]
	v_mfma_f32_16x16x32_bf16 v[120:123], v[184:187], v[210:213], v[120:123]
	v_mfma_f32_16x16x32_bf16 v[108:111], v[170:173], v[218:221], v[108:111]
	v_mfma_f32_16x16x32_bf16 v[104:107], v[184:187], v[218:221], v[104:107]
	v_mfma_f32_16x16x32_bf16 v[92:95], v[170:173], v[226:229], v[92:95]
	v_mfma_f32_16x16x32_bf16 v[88:91], v[184:187], v[226:229], v[88:91]
	v_mfma_f32_16x16x32_bf16 v[76:79], v[170:173], v[234:237], v[76:79]
	v_mfma_f32_16x16x32_bf16 v[72:75], v[184:187], v[234:237], v[72:75]
	s_setprio 0
	s_setprio 1
	v_mfma_f32_16x16x32_bf16 v[116:119], v[188:191], v[204:207], v[116:119]
	v_mfma_f32_16x16x32_bf16 v[112:115], v[196:199], v[204:207], v[112:115]
	v_mfma_f32_16x16x32_bf16 v[100:103], v[188:191], v[214:217], v[100:103]
	v_mfma_f32_16x16x32_bf16 v[96:99], v[196:199], v[214:217], v[96:99]
	v_mfma_f32_16x16x32_bf16 v[84:87], v[188:191], v[222:225], v[84:87]
	v_mfma_f32_16x16x32_bf16 v[80:83], v[196:199], v[222:225], v[80:83]
	v_mfma_f32_16x16x32_bf16 v[68:71], v[188:191], v[230:233], v[68:71]
	v_mfma_f32_16x16x32_bf16 v[64:67], v[196:199], v[230:233], v[64:67]
	v_mfma_f32_16x16x32_bf16 v[116:119], v[192:195], v[210:213], v[116:119]
	v_mfma_f32_16x16x32_bf16 v[112:115], v[200:203], v[210:213], v[112:115]
	v_mfma_f32_16x16x32_bf16 v[100:103], v[192:195], v[218:221], v[100:103]
	v_mfma_f32_16x16x32_bf16 v[96:99], v[200:203], v[218:221], v[96:99]
	v_mfma_f32_16x16x32_bf16 v[84:87], v[192:195], v[226:229], v[84:87]
	v_mfma_f32_16x16x32_bf16 v[80:83], v[200:203], v[226:229], v[80:83]
	v_mfma_f32_16x16x32_bf16 v[68:71], v[192:195], v[234:237], v[68:71]
	v_mfma_f32_16x16x32_bf16 v[64:67], v[200:203], v[234:237], v[64:67]
	s_setprio 0
	s_barrier
	s_add_i32 s77, s67, s52
	v_lshl_add_u64 v[174:175], s[36:37], 0, v[130:131]
	s_mov_b32 m0, s77
	ds_read_b128 v[204:207], v179 offset:16384
	ds_read_b128 v[210:213], v179 offset:17408
	ds_read_b128 v[214:217], v179 offset:18432
	ds_read_b128 v[218:221], v179 offset:19456
	ds_read_b128 v[222:225], v179 offset:20480
	ds_read_b128 v[226:229], v179 offset:21504
	ds_read_b128 v[230:233], v179 offset:22528
	ds_read_b128 v[234:237], v179 offset:23552
	global_load_lds_dwordx4 v[174:175], off
	s_add_i32 m0, s77, 0x2000
	s_add_u32 s80, s36, 0x100000
	v_lshl_add_u64 v[238:239], s[36:37], 0, v[134:135]
	s_addc_u32 s81, s37, 0
	s_add_i32 s77, s68, s52
	global_load_lds_dwordx4 v[238:239], off
	v_lshl_add_u64 v[240:241], s[80:81], 0, v[130:131]
	s_mov_b32 m0, s77
	v_lshl_add_u64 v[242:243], s[44:45], 0, v[132:133]
	global_load_lds_dwordx4 v[240:241], off
	v_lshl_add_u64 v[240:241], s[80:81], 0, v[134:135]
	s_add_i32 m0, s77, 0x2000
	s_nop 0
	global_load_lds_dwordx4 v[240:241], off
	v_lshl_add_u64 v[240:241], s[44:45], 0, v[128:129]
	s_mov_b32 m0, s53
	s_nop 0
	global_load_lds_dwordx4 v[240:241], off
	s_mov_b32 m0, s54
	s_nop 0
	global_load_lds_dwordx4 v[242:243], off
	s_waitcnt vmcnt(8)
	s_waitcnt lgkmcnt(0)
	s_barrier
	s_setprio 1
	s_waitcnt lgkmcnt(0)
	v_mfma_f32_16x16x32_bf16 v[60:63], v[166:169], v[204:207], v[60:63]
	v_mfma_f32_16x16x32_bf16 v[56:59], v[180:183], v[204:207], v[56:59]
	v_mfma_f32_16x16x32_bf16 v[44:47], v[166:169], v[214:217], v[44:47]
	v_mfma_f32_16x16x32_bf16 v[40:43], v[180:183], v[214:217], v[40:43]
	v_mfma_f32_16x16x32_bf16 v[28:31], v[166:169], v[222:225], v[28:31]
	v_mfma_f32_16x16x32_bf16 v[24:27], v[180:183], v[222:225], v[24:27]
	v_mfma_f32_16x16x32_bf16 v[12:15], v[166:169], v[230:233], v[12:15]
	v_mfma_f32_16x16x32_bf16 v[8:11], v[180:183], v[230:233], v[8:11]
	v_mfma_f32_16x16x32_bf16 v[60:63], v[170:173], v[210:213], v[60:63]
	v_mfma_f32_16x16x32_bf16 v[56:59], v[184:187], v[210:213], v[56:59]
	v_mfma_f32_16x16x32_bf16 v[44:47], v[170:173], v[218:221], v[44:47]
	v_mfma_f32_16x16x32_bf16 v[40:43], v[184:187], v[218:221], v[40:43]
	v_mfma_f32_16x16x32_bf16 v[28:31], v[170:173], v[226:229], v[28:31]
	v_mfma_f32_16x16x32_bf16 v[24:27], v[184:187], v[226:229], v[24:27]
	v_mfma_f32_16x16x32_bf16 v[12:15], v[170:173], v[234:237], v[12:15]
	v_mfma_f32_16x16x32_bf16 v[8:11], v[184:187], v[234:237], v[8:11]
	s_setprio 0
	s_setprio 1
	v_mfma_f32_16x16x32_bf16 v[52:55], v[188:191], v[204:207], v[52:55]
	v_mfma_f32_16x16x32_bf16 v[48:51], v[196:199], v[204:207], v[48:51]
	v_mfma_f32_16x16x32_bf16 v[36:39], v[188:191], v[214:217], v[36:39]
	v_mfma_f32_16x16x32_bf16 v[32:35], v[196:199], v[214:217], v[32:35]
	v_mfma_f32_16x16x32_bf16 v[20:23], v[188:191], v[222:225], v[20:23]
	v_mfma_f32_16x16x32_bf16 v[16:19], v[196:199], v[222:225], v[16:19]
	v_mfma_f32_16x16x32_bf16 v[4:7], v[188:191], v[230:233], v[4:7]
	v_mfma_f32_16x16x32_bf16 v[0:3], v[196:199], v[230:233], v[0:3]
	v_mfma_f32_16x16x32_bf16 v[52:55], v[192:195], v[210:213], v[52:55]
	v_mfma_f32_16x16x32_bf16 v[48:51], v[200:203], v[210:213], v[48:51]
	v_mfma_f32_16x16x32_bf16 v[36:39], v[192:195], v[218:221], v[36:39]
	v_mfma_f32_16x16x32_bf16 v[32:35], v[200:203], v[218:221], v[32:35]
	v_mfma_f32_16x16x32_bf16 v[20:23], v[192:195], v[226:229], v[20:23]
	v_mfma_f32_16x16x32_bf16 v[16:19], v[200:203], v[226:229], v[16:19]
	v_mfma_f32_16x16x32_bf16 v[4:7], v[192:195], v[234:237], v[4:7]
	v_mfma_f32_16x16x32_bf16 v[0:3], v[200:203], v[234:237], v[0:3]
	s_setprio 0
	s_barrier
	s_add_i32 s77, 0, 0x18000
	v_add_u32_e32 v136, s77, v176
	s_add_i32 s80, 0, 0x1c000
	ds_read_b128 v[166:169], v136
	ds_read_b128 v[170:173], v136 offset:1024
	ds_read_b128 v[180:183], v136 offset:2048
	ds_read_b128 v[184:187], v136 offset:3072
	v_add_u32_e32 v136, s80, v176
	ds_read_b128 v[188:191], v136
	ds_read_b128 v[192:195], v136 offset:1024
	ds_read_b128 v[196:199], v136 offset:2048
	ds_read_b128 v[200:203], v136 offset:3072
	s_add_u32 s44, s44, 0x100000
	s_addc_u32 s45, s45, 0
	s_mov_b32 m0, s55
	v_lshl_add_u64 v[244:245], s[44:45], 0, v[128:129]
	ds_read_b128 v[204:207], v179 offset:32768
	ds_read_b128 v[210:213], v179 offset:33792
	ds_read_b128 v[214:217], v179 offset:34816
	ds_read_b128 v[218:221], v179 offset:35840
	ds_read_b128 v[222:225], v179 offset:36864
	ds_read_b128 v[226:229], v179 offset:37888
	ds_read_b128 v[230:233], v179 offset:38912
	ds_read_b128 v[234:237], v179 offset:39936
	global_load_lds_dwordx4 v[244:245], off
	v_lshl_add_u64 v[244:245], s[44:45], 0, v[132:133]
	s_mov_b32 m0, s56
	s_nop 0
	global_load_lds_dwordx4 v[244:245], off
	s_waitcnt vmcnt(8)
	s_waitcnt lgkmcnt(0)
	s_barrier
	s_setprio 1
	s_waitcnt lgkmcnt(0)
	v_mfma_f32_16x16x32_bf16 v[124:127], v[166:169], v[204:207], v[124:127]
	v_mfma_f32_16x16x32_bf16 v[120:123], v[180:183], v[204:207], v[120:123]
	v_mfma_f32_16x16x32_bf16 v[108:111], v[166:169], v[214:217], v[108:111]
	v_mfma_f32_16x16x32_bf16 v[104:107], v[180:183], v[214:217], v[104:107]
	v_mfma_f32_16x16x32_bf16 v[92:95], v[166:169], v[222:225], v[92:95]
	v_mfma_f32_16x16x32_bf16 v[88:91], v[180:183], v[222:225], v[88:91]
	v_mfma_f32_16x16x32_bf16 v[76:79], v[166:169], v[230:233], v[76:79]
	v_mfma_f32_16x16x32_bf16 v[72:75], v[180:183], v[230:233], v[72:75]
	v_mfma_f32_16x16x32_bf16 v[124:127], v[170:173], v[210:213], v[124:127]
	v_mfma_f32_16x16x32_bf16 v[120:123], v[184:187], v[210:213], v[120:123]
	v_mfma_f32_16x16x32_bf16 v[108:111], v[170:173], v[218:221], v[108:111]
	v_mfma_f32_16x16x32_bf16 v[104:107], v[184:187], v[218:221], v[104:107]
	v_mfma_f32_16x16x32_bf16 v[92:95], v[170:173], v[226:229], v[92:95]
	v_mfma_f32_16x16x32_bf16 v[88:91], v[184:187], v[226:229], v[88:91]
	v_mfma_f32_16x16x32_bf16 v[76:79], v[170:173], v[234:237], v[76:79]
	v_mfma_f32_16x16x32_bf16 v[72:75], v[184:187], v[234:237], v[72:75]
	s_setprio 0
	s_setprio 1
	v_mfma_f32_16x16x32_bf16 v[116:119], v[188:191], v[204:207], v[116:119]
	v_mfma_f32_16x16x32_bf16 v[112:115], v[196:199], v[204:207], v[112:115]
	v_mfma_f32_16x16x32_bf16 v[100:103], v[188:191], v[214:217], v[100:103]
	v_mfma_f32_16x16x32_bf16 v[96:99], v[196:199], v[214:217], v[96:99]
	v_mfma_f32_16x16x32_bf16 v[84:87], v[188:191], v[222:225], v[84:87]
	v_mfma_f32_16x16x32_bf16 v[80:83], v[196:199], v[222:225], v[80:83]
	v_mfma_f32_16x16x32_bf16 v[68:71], v[188:191], v[230:233], v[68:71]
	v_mfma_f32_16x16x32_bf16 v[64:67], v[196:199], v[230:233], v[64:67]
	v_mfma_f32_16x16x32_bf16 v[116:119], v[192:195], v[210:213], v[116:119]
	v_mfma_f32_16x16x32_bf16 v[112:115], v[200:203], v[210:213], v[112:115]
	v_mfma_f32_16x16x32_bf16 v[100:103], v[192:195], v[218:221], v[100:103]
	v_mfma_f32_16x16x32_bf16 v[96:99], v[200:203], v[218:221], v[96:99]
	v_mfma_f32_16x16x32_bf16 v[84:87], v[192:195], v[226:229], v[84:87]
	v_mfma_f32_16x16x32_bf16 v[80:83], v[200:203], v[226:229], v[80:83]
	v_mfma_f32_16x16x32_bf16 v[68:71], v[192:195], v[234:237], v[68:71]
	v_mfma_f32_16x16x32_bf16 v[64:67], v[200:203], v[234:237], v[64:67]
	s_setprio 0
	s_barrier
	s_add_i32 s44, s77, s52
	v_lshl_add_u64 v[174:175], v[174:175], 0, s[16:17]
	s_mov_b32 m0, s44
	ds_read_b128 v[204:207], v179 offset:49152
	ds_read_b128 v[210:213], v179 offset:50176
	ds_read_b128 v[214:217], v179 offset:51200
	ds_read_b128 v[218:221], v179 offset:52224
	ds_read_b128 v[222:225], v179 offset:53248
	ds_read_b128 v[226:229], v179 offset:54272
	ds_read_b128 v[230:233], v179 offset:55296
	ds_read_b128 v[234:237], v179 offset:56320
	global_load_lds_dwordx4 v[174:175], off
	s_add_i32 m0, s44, 0x2000
	s_add_u32 s36, s36, 0x100080
	v_lshl_add_u64 v[174:175], v[238:239], 0, s[16:17]
	s_addc_u32 s37, s37, 0
	s_add_i32 s44, s80, s52
	global_load_lds_dwordx4 v[174:175], off
	v_lshl_add_u64 v[174:175], s[36:37], 0, v[130:131]
	s_mov_b32 m0, s44
	s_nop 0
	global_load_lds_dwordx4 v[174:175], off
	v_lshl_add_u64 v[174:175], s[36:37], 0, v[134:135]
	s_add_i32 m0, s44, 0x2000
	s_nop 0
	global_load_lds_dwordx4 v[174:175], off
	v_lshl_add_u64 v[174:175], v[240:241], 0, s[16:17]
	s_mov_b32 m0, s58
	s_nop 0
	global_load_lds_dwordx4 v[174:175], off
	v_lshl_add_u64 v[174:175], v[242:243], 0, s[16:17]
	s_mov_b32 m0, s59
	s_nop 0
	global_load_lds_dwordx4 v[174:175], off
	s_waitcnt vmcnt(8)
	s_waitcnt lgkmcnt(0)
	s_barrier
	s_setprio 1
	s_waitcnt lgkmcnt(0)
	v_mfma_f32_16x16x32_bf16 v[60:63], v[166:169], v[204:207], v[60:63]
	v_mfma_f32_16x16x32_bf16 v[56:59], v[180:183], v[204:207], v[56:59]
	v_mfma_f32_16x16x32_bf16 v[44:47], v[166:169], v[214:217], v[44:47]
	v_mfma_f32_16x16x32_bf16 v[40:43], v[180:183], v[214:217], v[40:43]
	v_mfma_f32_16x16x32_bf16 v[28:31], v[166:169], v[222:225], v[28:31]
	v_mfma_f32_16x16x32_bf16 v[24:27], v[180:183], v[222:225], v[24:27]
	v_mfma_f32_16x16x32_bf16 v[12:15], v[166:169], v[230:233], v[12:15]
	v_mfma_f32_16x16x32_bf16 v[8:11], v[180:183], v[230:233], v[8:11]
	v_mfma_f32_16x16x32_bf16 v[60:63], v[170:173], v[210:213], v[60:63]
	v_mfma_f32_16x16x32_bf16 v[56:59], v[184:187], v[210:213], v[56:59]
	v_mfma_f32_16x16x32_bf16 v[44:47], v[170:173], v[218:221], v[44:47]
	v_mfma_f32_16x16x32_bf16 v[40:43], v[184:187], v[218:221], v[40:43]
	v_mfma_f32_16x16x32_bf16 v[28:31], v[170:173], v[226:229], v[28:31]
	v_mfma_f32_16x16x32_bf16 v[24:27], v[184:187], v[226:229], v[24:27]
	v_mfma_f32_16x16x32_bf16 v[12:15], v[170:173], v[234:237], v[12:15]
	v_mfma_f32_16x16x32_bf16 v[8:11], v[184:187], v[234:237], v[8:11]
	s_setprio 0
	s_setprio 1
	v_mfma_f32_16x16x32_bf16 v[52:55], v[188:191], v[204:207], v[52:55]
	v_mfma_f32_16x16x32_bf16 v[48:51], v[196:199], v[204:207], v[48:51]
	v_mfma_f32_16x16x32_bf16 v[36:39], v[188:191], v[214:217], v[36:39]
	v_mfma_f32_16x16x32_bf16 v[32:35], v[196:199], v[214:217], v[32:35]
	v_mfma_f32_16x16x32_bf16 v[20:23], v[188:191], v[222:225], v[20:23]
	v_mfma_f32_16x16x32_bf16 v[16:19], v[196:199], v[222:225], v[16:19]
	v_mfma_f32_16x16x32_bf16 v[4:7], v[188:191], v[230:233], v[4:7]
	v_mfma_f32_16x16x32_bf16 v[0:3], v[196:199], v[230:233], v[0:3]
	v_mfma_f32_16x16x32_bf16 v[52:55], v[192:195], v[210:213], v[52:55]
	v_mfma_f32_16x16x32_bf16 v[48:51], v[200:203], v[210:213], v[48:51]
	v_mfma_f32_16x16x32_bf16 v[36:39], v[192:195], v[218:221], v[36:39]
	v_mfma_f32_16x16x32_bf16 v[32:35], v[200:203], v[218:221], v[32:35]
	v_mfma_f32_16x16x32_bf16 v[20:23], v[192:195], v[226:229], v[20:23]
	v_mfma_f32_16x16x32_bf16 v[16:19], v[200:203], v[226:229], v[16:19]
	v_mfma_f32_16x16x32_bf16 v[4:7], v[192:195], v[234:237], v[4:7]
	v_mfma_f32_16x16x32_bf16 v[0:3], v[200:203], v[234:237], v[0:3]
	s_setprio 0
	s_add_u32 s34, s34, 0x100
	s_addc_u32 s35, s35, 0
	s_add_u32 s30, s30, 0x100
	s_addc_u32 s31, s31, 0
	s_cmp_ge_u32 s71, s9
	s_mov_b32 s36, s71
	s_barrier
	s_cbranch_scc0 .LBB0_875
	s_and_b64 vcc, exec, s[18:19]
	s_cbranch_vccz .LBB0_878
	s_barrier

.LBB0_1089:
	ds_read_b128 v[144:147], v155
	ds_read_b128 v[148:151], v155 offset:1024
	ds_read_b128 v[158:161], v155 offset:2048
	ds_read_b128 v[162:165], v155 offset:3072
	ds_read_b128 v[166:169], v156
	ds_read_b128 v[170:173], v156 offset:1024
	ds_read_b128 v[174:177], v156 offset:2048
	ds_read_b128 v[178:181], v156 offset:3072
	s_add_u32 s35, s36, 0xfffc0080
	s_addc_u32 s52, s37, -1
	s_cmp_eq_u32 s31, 12
	s_cselect_b32 s55, s1, s52
	s_cselect_b32 s54, s0, s35
	s_cselect_b32 s53, s45, s30
	s_cselect_b32 s52, s44, s9
	v_lshl_add_u64 v[206:207], s[36:37], 0, v[136:137]
	s_add_i32 m0, s56, 0xc000
	ds_read_b128 v[182:185], v157
	ds_read_b128 v[186:189], v157 offset:1024
	ds_read_b128 v[190:193], v157 offset:2048
	ds_read_b128 v[194:197], v157 offset:3072
	ds_read_b128 v[198:201], v157 offset:4096
	ds_read_b128 v[202:205], v157 offset:5120
	ds_read_b128 v[210:213], v157 offset:6144
	ds_read_b128 v[214:217], v157 offset:7168
	global_load_lds_dwordx4 v[206:207], off
	v_lshl_add_u64 v[206:207], s[36:37], 0, v[138:139]
	s_add_i32 m0, s56, 0xe000
	s_nop 0
	global_load_lds_dwordx4 v[206:207], off
	s_waitcnt vmcnt(8)
	s_waitcnt lgkmcnt(0)
	s_barrier
	s_setprio 1
	s_waitcnt lgkmcnt(0)
	v_mfma_f32_16x16x32_bf16 v[124:127], v[144:147], v[182:185], v[124:127]
	v_mfma_f32_16x16x32_bf16 v[120:123], v[158:161], v[182:185], v[120:123]
	v_mfma_f32_16x16x32_bf16 v[108:111], v[144:147], v[190:193], v[108:111]
	v_mfma_f32_16x16x32_bf16 v[104:107], v[158:161], v[190:193], v[104:107]
	v_mfma_f32_16x16x32_bf16 v[92:95], v[144:147], v[198:201], v[92:95]
	v_mfma_f32_16x16x32_bf16 v[88:91], v[158:161], v[198:201], v[88:91]
	v_mfma_f32_16x16x32_bf16 v[76:79], v[144:147], v[210:213], v[76:79]
	v_mfma_f32_16x16x32_bf16 v[72:75], v[158:161], v[210:213], v[72:75]
	v_mfma_f32_16x16x32_bf16 v[124:127], v[148:151], v[186:189], v[124:127]
	v_mfma_f32_16x16x32_bf16 v[120:123], v[162:165], v[186:189], v[120:123]
	v_mfma_f32_16x16x32_bf16 v[108:111], v[148:151], v[194:197], v[108:111]
	v_mfma_f32_16x16x32_bf16 v[104:107], v[162:165], v[194:197], v[104:107]
	v_mfma_f32_16x16x32_bf16 v[92:95], v[148:151], v[202:205], v[92:95]
	v_mfma_f32_16x16x32_bf16 v[88:91], v[162:165], v[202:205], v[88:91]
	v_mfma_f32_16x16x32_bf16 v[76:79], v[148:151], v[214:217], v[76:79]
	v_mfma_f32_16x16x32_bf16 v[72:75], v[162:165], v[214:217], v[72:75]
	s_setprio 0
	s_setprio 1
	v_mfma_f32_16x16x32_bf16 v[116:119], v[166:169], v[182:185], v[116:119]
	v_mfma_f32_16x16x32_bf16 v[112:115], v[174:177], v[182:185], v[112:115]
	v_mfma_f32_16x16x32_bf16 v[100:103], v[166:169], v[190:193], v[100:103]
	v_mfma_f32_16x16x32_bf16 v[96:99], v[174:177], v[190:193], v[96:99]
	v_mfma_f32_16x16x32_bf16 v[84:87], v[166:169], v[198:201], v[84:87]
	v_mfma_f32_16x16x32_bf16 v[80:83], v[174:177], v[198:201], v[80:83]
	v_mfma_f32_16x16x32_bf16 v[68:71], v[166:169], v[210:213], v[68:71]
	v_mfma_f32_16x16x32_bf16 v[64:67], v[174:177], v[210:213], v[64:67]
	v_mfma_f32_16x16x32_bf16 v[116:119], v[170:173], v[186:189], v[116:119]
	v_mfma_f32_16x16x32_bf16 v[112:115], v[178:181], v[186:189], v[112:115]
	v_mfma_f32_16x16x32_bf16 v[100:103], v[170:173], v[194:197], v[100:103]
	v_mfma_f32_16x16x32_bf16 v[96:99], v[178:181], v[194:197], v[96:99]
	v_mfma_f32_16x16x32_bf16 v[84:87], v[170:173], v[202:205], v[84:87]
	v_mfma_f32_16x16x32_bf16 v[80:83], v[178:181], v[202:205], v[80:83]
	v_mfma_f32_16x16x32_bf16 v[68:71], v[170:173], v[214:217], v[68:71]
	v_mfma_f32_16x16x32_bf16 v[64:67], v[178:181], v[214:217], v[64:67]
	s_setprio 0
	s_barrier
	s_add_i32 s35, s71, s23
	v_lshl_add_u64 v[206:207], s[52:53], 0, v[130:131]
	s_mov_b32 m0, s35
	ds_read_b128 v[182:185], v157 offset:16384
	ds_read_b128 v[186:189], v157 offset:17408
	ds_read_b128 v[190:193], v157 offset:18432
	ds_read_b128 v[194:197], v157 offset:19456
	ds_read_b128 v[198:201], v157 offset:20480
	ds_read_b128 v[202:205], v157 offset:21504
	ds_read_b128 v[210:213], v157 offset:22528
	ds_read_b128 v[214:217], v157 offset:23552
	global_load_lds_dwordx4 v[206:207], off
	s_add_i32 m0, s35, 0x2000
	s_add_u32 s82, s52, 0x40000
	v_lshl_add_u64 v[218:219], s[52:53], 0, v[134:135]
	s_addc_u32 s83, s53, 0
	s_add_i32 s35, s77, s23
	global_load_lds_dwordx4 v[218:219], off
	v_lshl_add_u64 v[220:221], s[82:83], 0, v[130:131]
	s_mov_b32 m0, s35
	v_lshl_add_u64 v[222:223], s[54:55], 0, v[132:133]
	global_load_lds_dwordx4 v[220:221], off
	v_lshl_add_u64 v[220:221], s[82:83], 0, v[134:135]
	s_add_i32 m0, s35, 0x2000
	s_nop 0
	global_load_lds_dwordx4 v[220:221], off
	v_lshl_add_u64 v[220:221], s[54:55], 0, v[128:129]
	s_mov_b32 m0, s56
	s_nop 0
	global_load_lds_dwordx4 v[220:221], off
	s_mov_b32 m0, s57
	s_nop 0
	global_load_lds_dwordx4 v[222:223], off
	s_waitcnt vmcnt(8)
	s_waitcnt lgkmcnt(0)
	s_barrier
	s_setprio 1
	s_waitcnt lgkmcnt(0)
	v_mfma_f32_16x16x32_bf16 v[60:63], v[144:147], v[182:185], v[60:63]
	v_mfma_f32_16x16x32_bf16 v[56:59], v[158:161], v[182:185], v[56:59]
	v_mfma_f32_16x16x32_bf16 v[44:47], v[144:147], v[190:193], v[44:47]
	v_mfma_f32_16x16x32_bf16 v[40:43], v[158:161], v[190:193], v[40:43]
	v_mfma_f32_16x16x32_bf16 v[28:31], v[144:147], v[198:201], v[28:31]
	v_mfma_f32_16x16x32_bf16 v[24:27], v[158:161], v[198:201], v[24:27]
	v_mfma_f32_16x16x32_bf16 v[12:15], v[144:147], v[210:213], v[12:15]
	v_mfma_f32_16x16x32_bf16 v[8:11], v[158:161], v[210:213], v[8:11]
	v_mfma_f32_16x16x32_bf16 v[60:63], v[148:151], v[186:189], v[60:63]
	v_mfma_f32_16x16x32_bf16 v[56:59], v[162:165], v[186:189], v[56:59]
	v_mfma_f32_16x16x32_bf16 v[44:47], v[148:151], v[194:197], v[44:47]
	v_mfma_f32_16x16x32_bf16 v[40:43], v[162:165], v[194:197], v[40:43]
	v_mfma_f32_16x16x32_bf16 v[28:31], v[148:151], v[202:205], v[28:31]
	v_mfma_f32_16x16x32_bf16 v[24:27], v[162:165], v[202:205], v[24:27]
	v_mfma_f32_16x16x32_bf16 v[12:15], v[148:151], v[214:217], v[12:15]
	v_mfma_f32_16x16x32_bf16 v[8:11], v[162:165], v[214:217], v[8:11]
	s_setprio 0
	s_setprio 1
	v_mfma_f32_16x16x32_bf16 v[52:55], v[166:169], v[182:185], v[52:55]
	v_mfma_f32_16x16x32_bf16 v[48:51], v[174:177], v[182:185], v[48:51]
	v_mfma_f32_16x16x32_bf16 v[36:39], v[166:169], v[190:193], v[36:39]
	v_mfma_f32_16x16x32_bf16 v[32:35], v[174:177], v[190:193], v[32:35]
	v_mfma_f32_16x16x32_bf16 v[20:23], v[166:169], v[198:201], v[20:23]
	v_mfma_f32_16x16x32_bf16 v[16:19], v[174:177], v[198:201], v[16:19]
	v_mfma_f32_16x16x32_bf16 v[4:7], v[166:169], v[210:213], v[4:7]
	v_mfma_f32_16x16x32_bf16 v[0:3], v[174:177], v[210:213], v[0:3]
	v_mfma_f32_16x16x32_bf16 v[52:55], v[170:173], v[186:189], v[52:55]
	v_mfma_f32_16x16x32_bf16 v[48:51], v[178:181], v[186:189], v[48:51]
	v_mfma_f32_16x16x32_bf16 v[36:39], v[170:173], v[194:197], v[36:39]
	v_mfma_f32_16x16x32_bf16 v[32:35], v[178:181], v[194:197], v[32:35]
	v_mfma_f32_16x16x32_bf16 v[20:23], v[170:173], v[202:205], v[20:23]
	v_mfma_f32_16x16x32_bf16 v[16:19], v[178:181], v[202:205], v[16:19]
	v_mfma_f32_16x16x32_bf16 v[4:7], v[170:173], v[214:217], v[4:7]
	v_mfma_f32_16x16x32_bf16 v[0:3], v[178:181], v[214:217], v[0:3]
	s_setprio 0
	s_barrier
	s_add_i32 s35, 0, 0x18000
	s_add_i32 s82, 0, 0x1c000
	v_add_u32_e32 v162, s35, v153
	v_add_u32_e32 v178, s82, v153
	ds_read_b128 v[144:147], v162
	ds_read_b128 v[148:151], v162 offset:1024
	ds_read_b128 v[158:161], v162 offset:2048
	ds_read_b128 v[162:165], v162 offset:3072
	ds_read_b128 v[166:169], v178
	ds_read_b128 v[170:173], v178 offset:1024
	ds_read_b128 v[174:177], v178 offset:2048
	ds_read_b128 v[178:181], v178 offset:3072
	s_add_u32 s54, s54, 0x40000
	s_addc_u32 s55, s55, 0
	s_mov_b32 m0, s58
	v_lshl_add_u64 v[224:225], s[54:55], 0, v[128:129]
	ds_read_b128 v[182:185], v157 offset:32768
	ds_read_b128 v[186:189], v157 offset:33792
	ds_read_b128 v[190:193], v157 offset:34816
	ds_read_b128 v[194:197], v157 offset:35840
	ds_read_b128 v[198:201], v157 offset:36864
	ds_read_b128 v[202:205], v157 offset:37888
	ds_read_b128 v[210:213], v157 offset:38912
	ds_read_b128 v[214:217], v157 offset:39936
	global_load_lds_dwordx4 v[224:225], off
	v_lshl_add_u64 v[224:225], s[54:55], 0, v[132:133]
	s_mov_b32 m0, s59
	s_nop 0
	global_load_lds_dwordx4 v[224:225], off
	s_waitcnt vmcnt(8)
	s_waitcnt lgkmcnt(0)
	s_barrier
	s_setprio 1
	s_waitcnt lgkmcnt(0)
	v_mfma_f32_16x16x32_bf16 v[124:127], v[144:147], v[182:185], v[124:127]
	v_mfma_f32_16x16x32_bf16 v[120:123], v[158:161], v[182:185], v[120:123]
	v_mfma_f32_16x16x32_bf16 v[108:111], v[144:147], v[190:193], v[108:111]
	v_mfma_f32_16x16x32_bf16 v[104:107], v[158:161], v[190:193], v[104:107]
	v_mfma_f32_16x16x32_bf16 v[92:95], v[144:147], v[198:201], v[92:95]
	v_mfma_f32_16x16x32_bf16 v[88:91], v[158:161], v[198:201], v[88:91]
	v_mfma_f32_16x16x32_bf16 v[76:79], v[144:147], v[210:213], v[76:79]
	v_mfma_f32_16x16x32_bf16 v[72:75], v[158:161], v[210:213], v[72:75]
	v_mfma_f32_16x16x32_bf16 v[124:127], v[148:151], v[186:189], v[124:127]
	v_mfma_f32_16x16x32_bf16 v[120:123], v[162:165], v[186:189], v[120:123]
	v_mfma_f32_16x16x32_bf16 v[108:111], v[148:151], v[194:197], v[108:111]
	v_mfma_f32_16x16x32_bf16 v[104:107], v[162:165], v[194:197], v[104:107]
	v_mfma_f32_16x16x32_bf16 v[92:95], v[148:151], v[202:205], v[92:95]
	v_mfma_f32_16x16x32_bf16 v[88:91], v[162:165], v[202:205], v[88:91]
	v_mfma_f32_16x16x32_bf16 v[76:79], v[148:151], v[214:217], v[76:79]
	v_mfma_f32_16x16x32_bf16 v[72:75], v[162:165], v[214:217], v[72:75]
	s_setprio 0
	s_setprio 1
	v_mfma_f32_16x16x32_bf16 v[116:119], v[166:169], v[182:185], v[116:119]
	v_mfma_f32_16x16x32_bf16 v[112:115], v[174:177], v[182:185], v[112:115]
	v_mfma_f32_16x16x32_bf16 v[100:103], v[166:169], v[190:193], v[100:103]
	v_mfma_f32_16x16x32_bf16 v[96:99], v[174:177], v[190:193], v[96:99]
	v_mfma_f32_16x16x32_bf16 v[84:87], v[166:169], v[198:201], v[84:87]
	v_mfma_f32_16x16x32_bf16 v[80:83], v[174:177], v[198:201], v[80:83]
	v_mfma_f32_16x16x32_bf16 v[68:71], v[166:169], v[210:213], v[68:71]
	v_mfma_f32_16x16x32_bf16 v[64:67], v[174:177], v[210:213], v[64:67]
	v_mfma_f32_16x16x32_bf16 v[116:119], v[170:173], v[186:189], v[116:119]
	v_mfma_f32_16x16x32_bf16 v[112:115], v[178:181], v[186:189], v[112:115]
	v_mfma_f32_16x16x32_bf16 v[100:103], v[170:173], v[194:197], v[100:103]
	v_mfma_f32_16x16x32_bf16 v[96:99], v[178:181], v[194:197], v[96:99]
	v_mfma_f32_16x16x32_bf16 v[84:87], v[170:173], v[202:205], v[84:87]
	v_mfma_f32_16x16x32_bf16 v[80:83], v[178:181], v[202:205], v[80:83]
	v_mfma_f32_16x16x32_bf16 v[68:71], v[170:173], v[214:217], v[68:71]
	v_mfma_f32_16x16x32_bf16 v[64:67], v[178:181], v[214:217], v[64:67]
	s_setprio 0
	s_barrier
	s_add_i32 s35, s35, s23
	v_lshl_add_u64 v[206:207], v[206:207], 0, s[18:19]
	s_mov_b32 m0, s35
	ds_read_b128 v[182:185], v157 offset:49152
	ds_read_b128 v[186:189], v157 offset:50176
	ds_read_b128 v[190:193], v157 offset:51200
	ds_read_b128 v[194:197], v157 offset:52224
	ds_read_b128 v[198:201], v157 offset:53248
	ds_read_b128 v[202:205], v157 offset:54272
	ds_read_b128 v[210:213], v157 offset:55296
	ds_read_b128 v[214:217], v157 offset:56320
	global_load_lds_dwordx4 v[206:207], off
	s_add_i32 m0, s35, 0x2000
	s_add_u32 s52, s52, 0x40080
	v_lshl_add_u64 v[206:207], v[218:219], 0, s[18:19]
	s_addc_u32 s53, s53, 0
	s_add_i32 s35, s82, s23
	global_load_lds_dwordx4 v[206:207], off
	v_lshl_add_u64 v[206:207], s[52:53], 0, v[130:131]
	s_mov_b32 m0, s35
	s_nop 0
	global_load_lds_dwordx4 v[206:207], off
	v_lshl_add_u64 v[206:207], s[52:53], 0, v[134:135]
	s_add_i32 m0, s35, 0x2000
	s_nop 0
	global_load_lds_dwordx4 v[206:207], off
	v_lshl_add_u64 v[206:207], v[220:221], 0, s[18:19]
	s_mov_b32 m0, s66
	s_nop 0
	global_load_lds_dwordx4 v[206:207], off
	v_lshl_add_u64 v[206:207], v[222:223], 0, s[18:19]
	s_mov_b32 m0, s67
	s_nop 0
	global_load_lds_dwordx4 v[206:207], off
	s_waitcnt vmcnt(8)
	s_waitcnt lgkmcnt(0)
	s_barrier
	s_setprio 1
	s_waitcnt lgkmcnt(0)
	v_mfma_f32_16x16x32_bf16 v[60:63], v[144:147], v[182:185], v[60:63]
	v_mfma_f32_16x16x32_bf16 v[56:59], v[158:161], v[182:185], v[56:59]
	v_mfma_f32_16x16x32_bf16 v[44:47], v[144:147], v[190:193], v[44:47]
	v_mfma_f32_16x16x32_bf16 v[40:43], v[158:161], v[190:193], v[40:43]
	v_mfma_f32_16x16x32_bf16 v[28:31], v[144:147], v[198:201], v[28:31]
	v_mfma_f32_16x16x32_bf16 v[24:27], v[158:161], v[198:201], v[24:27]
	v_mfma_f32_16x16x32_bf16 v[12:15], v[144:147], v[210:213], v[12:15]
	v_mfma_f32_16x16x32_bf16 v[8:11], v[158:161], v[210:213], v[8:11]
	v_mfma_f32_16x16x32_bf16 v[60:63], v[148:151], v[186:189], v[60:63]
	v_mfma_f32_16x16x32_bf16 v[56:59], v[162:165], v[186:189], v[56:59]
	v_mfma_f32_16x16x32_bf16 v[44:47], v[148:151], v[194:197], v[44:47]
	v_mfma_f32_16x16x32_bf16 v[40:43], v[162:165], v[194:197], v[40:43]
	v_mfma_f32_16x16x32_bf16 v[28:31], v[148:151], v[202:205], v[28:31]
	v_mfma_f32_16x16x32_bf16 v[24:27], v[162:165], v[202:205], v[24:27]
	v_mfma_f32_16x16x32_bf16 v[12:15], v[148:151], v[214:217], v[12:15]
	v_mfma_f32_16x16x32_bf16 v[8:11], v[162:165], v[214:217], v[8:11]
	s_setprio 0
	s_setprio 1
	v_mfma_f32_16x16x32_bf16 v[52:55], v[166:169], v[182:185], v[52:55]
	v_mfma_f32_16x16x32_bf16 v[48:51], v[174:177], v[182:185], v[48:51]
	v_mfma_f32_16x16x32_bf16 v[36:39], v[166:169], v[190:193], v[36:39]
	v_mfma_f32_16x16x32_bf16 v[32:35], v[174:177], v[190:193], v[32:35]
	v_mfma_f32_16x16x32_bf16 v[20:23], v[166:169], v[198:201], v[20:23]
	v_mfma_f32_16x16x32_bf16 v[16:19], v[174:177], v[198:201], v[16:19]
	v_mfma_f32_16x16x32_bf16 v[4:7], v[166:169], v[210:213], v[4:7]
	v_mfma_f32_16x16x32_bf16 v[0:3], v[174:177], v[210:213], v[0:3]
	v_mfma_f32_16x16x32_bf16 v[52:55], v[170:173], v[186:189], v[52:55]
	v_mfma_f32_16x16x32_bf16 v[48:51], v[178:181], v[186:189], v[48:51]
	v_mfma_f32_16x16x32_bf16 v[36:39], v[170:173], v[194:197], v[36:39]
	v_mfma_f32_16x16x32_bf16 v[32:35], v[178:181], v[194:197], v[32:35]
	v_mfma_f32_16x16x32_bf16 v[20:23], v[170:173], v[202:205], v[20:23]
	v_mfma_f32_16x16x32_bf16 v[16:19], v[178:181], v[202:205], v[16:19]
	v_mfma_f32_16x16x32_bf16 v[4:7], v[170:173], v[214:217], v[4:7]
	v_mfma_f32_16x16x32_bf16 v[0:3], v[178:181], v[214:217], v[0:3]
	s_setprio 0
	s_add_i32 s31, s31, 2
	s_add_u32 s36, s36, 0x100
	s_addc_u32 s37, s37, 0
	s_add_u32 s9, s9, 0x100
	s_addc_u32 s30, s30, 0
	s_cmp_gt_u32 s31, 13
	s_barrier
	s_cbranch_scc0 .LBB0_1089
	s_and_b64 vcc, exec, s[20:21]
	s_cbranch_vccz .LBB0_1092
	s_barrier

.LBB0_1493:
	ds_read_b128 v[166:169], v183
	ds_read_b128 v[170:173], v183 offset:1024
	ds_read_b128 v[186:189], v183 offset:2048
	ds_read_b128 v[190:193], v183 offset:3072
	ds_read_b128 v[194:197], v184
	ds_read_b128 v[198:201], v184 offset:1024
	ds_read_b128 v[202:205], v184 offset:2048
	ds_read_b128 v[210:213], v184 offset:3072
	s_add_i32 s62, s40, 2
	s_add_u32 s41, s36, 0xfffc0080
	s_addc_u32 s42, s37, -1
	s_cmp_eq_u32 s29, s40
	s_cselect_b32 s40, s34, s30
	s_cselect_b32 s43, s1, s42
	s_cselect_b32 s42, s0, s41
	s_cselect_b32 s41, s35, s31
	v_lshl_add_u64 v[174:175], s[36:37], 0, v[156:157]
	s_add_i32 m0, s44, 0xc000
	ds_read_b128 v[214:217], v185
	ds_read_b128 v[218:221], v185 offset:1024
	ds_read_b128 v[222:225], v185 offset:2048
	ds_read_b128 v[226:229], v185 offset:3072
	ds_read_b128 v[230:233], v185 offset:4096
	ds_read_b128 v[234:237], v185 offset:5120
	ds_read_b128 v[238:241], v185 offset:6144
	ds_read_b128 v[242:245], v185 offset:7168
	global_load_lds_dwordx4 v[174:175], off
	v_lshl_add_u64 v[174:175], s[36:37], 0, v[158:159]
	s_add_i32 m0, s44, 0xe000
	s_nop 0
	global_load_lds_dwordx4 v[174:175], off
	s_waitcnt vmcnt(8)
	s_waitcnt lgkmcnt(0)
	s_barrier
	s_setprio 1
	s_waitcnt lgkmcnt(0)
	v_mfma_f32_16x16x32_bf16 v[124:127], v[166:169], v[214:217], v[124:127]
	v_mfma_f32_16x16x32_bf16 v[120:123], v[186:189], v[214:217], v[120:123]
	v_mfma_f32_16x16x32_bf16 v[108:111], v[166:169], v[222:225], v[108:111]
	v_mfma_f32_16x16x32_bf16 v[104:107], v[186:189], v[222:225], v[104:107]
	v_mfma_f32_16x16x32_bf16 v[92:95], v[166:169], v[230:233], v[92:95]
	v_mfma_f32_16x16x32_bf16 v[88:91], v[186:189], v[230:233], v[88:91]
	v_mfma_f32_16x16x32_bf16 v[76:79], v[166:169], v[238:241], v[76:79]
	v_mfma_f32_16x16x32_bf16 v[72:75], v[186:189], v[238:241], v[72:75]
	v_mfma_f32_16x16x32_bf16 v[124:127], v[170:173], v[218:221], v[124:127]
	v_mfma_f32_16x16x32_bf16 v[120:123], v[190:193], v[218:221], v[120:123]
	v_mfma_f32_16x16x32_bf16 v[108:111], v[170:173], v[226:229], v[108:111]
	v_mfma_f32_16x16x32_bf16 v[104:107], v[190:193], v[226:229], v[104:107]
	v_mfma_f32_16x16x32_bf16 v[92:95], v[170:173], v[234:237], v[92:95]
	v_mfma_f32_16x16x32_bf16 v[88:91], v[190:193], v[234:237], v[88:91]
	v_mfma_f32_16x16x32_bf16 v[76:79], v[170:173], v[242:245], v[76:79]
	v_mfma_f32_16x16x32_bf16 v[72:75], v[190:193], v[242:245], v[72:75]
	s_setprio 0
	s_setprio 1
	v_mfma_f32_16x16x32_bf16 v[116:119], v[194:197], v[214:217], v[116:119]
	v_mfma_f32_16x16x32_bf16 v[112:115], v[202:205], v[214:217], v[112:115]
	v_mfma_f32_16x16x32_bf16 v[100:103], v[194:197], v[222:225], v[100:103]
	v_mfma_f32_16x16x32_bf16 v[96:99], v[202:205], v[222:225], v[96:99]
	v_mfma_f32_16x16x32_bf16 v[84:87], v[194:197], v[230:233], v[84:87]
	v_mfma_f32_16x16x32_bf16 v[80:83], v[202:205], v[230:233], v[80:83]
	v_mfma_f32_16x16x32_bf16 v[68:71], v[194:197], v[238:241], v[68:71]
	v_mfma_f32_16x16x32_bf16 v[64:67], v[202:205], v[238:241], v[64:67]
	v_mfma_f32_16x16x32_bf16 v[116:119], v[198:201], v[218:221], v[116:119]
	v_mfma_f32_16x16x32_bf16 v[112:115], v[210:213], v[218:221], v[112:115]
	v_mfma_f32_16x16x32_bf16 v[100:103], v[198:201], v[226:229], v[100:103]
	v_mfma_f32_16x16x32_bf16 v[96:99], v[210:213], v[226:229], v[96:99]
	v_mfma_f32_16x16x32_bf16 v[84:87], v[198:201], v[234:237], v[84:87]
	v_mfma_f32_16x16x32_bf16 v[80:83], v[210:213], v[234:237], v[80:83]
	v_mfma_f32_16x16x32_bf16 v[68:71], v[198:201], v[242:245], v[68:71]
	v_mfma_f32_16x16x32_bf16 v[64:67], v[210:213], v[242:245], v[64:67]
	s_setprio 0
	s_barrier
	s_add_i32 s63, s55, s2
	v_lshl_add_u64 v[174:175], s[40:41], 0, v[130:131]
	s_mov_b32 m0, s63
	ds_read_b128 v[214:217], v185 offset:16384
	ds_read_b128 v[218:221], v185 offset:17408
	ds_read_b128 v[222:225], v185 offset:18432
	ds_read_b128 v[226:229], v185 offset:19456
	ds_read_b128 v[230:233], v185 offset:20480
	ds_read_b128 v[234:237], v185 offset:21504
	ds_read_b128 v[238:241], v185 offset:22528
	ds_read_b128 v[242:245], v185 offset:23552
	global_load_lds_dwordx4 v[174:175], off
	s_add_i32 m0, s63, 0x2000
	s_add_u32 s64, s40, 0x40000
	v_lshl_add_u64 v[206:207], s[40:41], 0, v[134:135]
	s_addc_u32 s65, s41, 0
	s_add_i32 s63, s56, s2
	global_load_lds_dwordx4 v[206:207], off
	v_lshl_add_u64 v[246:247], s[64:65], 0, v[130:131]
	s_mov_b32 m0, s63
	v_lshl_add_u64 v[248:249], s[42:43], 0, v[132:133]
	global_load_lds_dwordx4 v[246:247], off
	v_lshl_add_u64 v[246:247], s[64:65], 0, v[134:135]
	s_add_i32 m0, s63, 0x2000
	s_nop 0
	global_load_lds_dwordx4 v[246:247], off
	v_lshl_add_u64 v[246:247], s[42:43], 0, v[128:129]
	s_mov_b32 m0, s44
	s_nop 0
	global_load_lds_dwordx4 v[246:247], off
	s_mov_b32 m0, s45
	s_nop 0
	global_load_lds_dwordx4 v[248:249], off
	s_waitcnt vmcnt(8)
	s_waitcnt lgkmcnt(0)
	s_barrier
	s_setprio 1
	s_waitcnt lgkmcnt(0)
	v_mfma_f32_16x16x32_bf16 v[60:63], v[166:169], v[214:217], v[60:63]
	v_mfma_f32_16x16x32_bf16 v[56:59], v[186:189], v[214:217], v[56:59]
	v_mfma_f32_16x16x32_bf16 v[44:47], v[166:169], v[222:225], v[44:47]
	v_mfma_f32_16x16x32_bf16 v[40:43], v[186:189], v[222:225], v[40:43]
	v_mfma_f32_16x16x32_bf16 v[28:31], v[166:169], v[230:233], v[28:31]
	v_mfma_f32_16x16x32_bf16 v[24:27], v[186:189], v[230:233], v[24:27]
	v_mfma_f32_16x16x32_bf16 v[12:15], v[166:169], v[238:241], v[12:15]
	v_mfma_f32_16x16x32_bf16 v[8:11], v[186:189], v[238:241], v[8:11]
	v_mfma_f32_16x16x32_bf16 v[60:63], v[170:173], v[218:221], v[60:63]
	v_mfma_f32_16x16x32_bf16 v[56:59], v[190:193], v[218:221], v[56:59]
	v_mfma_f32_16x16x32_bf16 v[44:47], v[170:173], v[226:229], v[44:47]
	v_mfma_f32_16x16x32_bf16 v[40:43], v[190:193], v[226:229], v[40:43]
	v_mfma_f32_16x16x32_bf16 v[28:31], v[170:173], v[234:237], v[28:31]
	v_mfma_f32_16x16x32_bf16 v[24:27], v[190:193], v[234:237], v[24:27]
	v_mfma_f32_16x16x32_bf16 v[12:15], v[170:173], v[242:245], v[12:15]
	v_mfma_f32_16x16x32_bf16 v[8:11], v[190:193], v[242:245], v[8:11]
	s_setprio 0
	s_setprio 1
	v_mfma_f32_16x16x32_bf16 v[52:55], v[194:197], v[214:217], v[52:55]
	v_mfma_f32_16x16x32_bf16 v[48:51], v[202:205], v[214:217], v[48:51]
	v_mfma_f32_16x16x32_bf16 v[36:39], v[194:197], v[222:225], v[36:39]
	v_mfma_f32_16x16x32_bf16 v[32:35], v[202:205], v[222:225], v[32:35]
	v_mfma_f32_16x16x32_bf16 v[20:23], v[194:197], v[230:233], v[20:23]
	v_mfma_f32_16x16x32_bf16 v[16:19], v[202:205], v[230:233], v[16:19]
	v_mfma_f32_16x16x32_bf16 v[4:7], v[194:197], v[238:241], v[4:7]
	v_mfma_f32_16x16x32_bf16 v[0:3], v[202:205], v[238:241], v[0:3]
	v_mfma_f32_16x16x32_bf16 v[52:55], v[198:201], v[218:221], v[52:55]
	v_mfma_f32_16x16x32_bf16 v[48:51], v[210:213], v[218:221], v[48:51]
	v_mfma_f32_16x16x32_bf16 v[36:39], v[198:201], v[226:229], v[36:39]
	v_mfma_f32_16x16x32_bf16 v[32:35], v[210:213], v[226:229], v[32:35]
	v_mfma_f32_16x16x32_bf16 v[20:23], v[198:201], v[234:237], v[20:23]
	v_mfma_f32_16x16x32_bf16 v[16:19], v[210:213], v[234:237], v[16:19]
	v_mfma_f32_16x16x32_bf16 v[4:7], v[198:201], v[242:245], v[4:7]
	v_mfma_f32_16x16x32_bf16 v[0:3], v[210:213], v[242:245], v[0:3]
	s_setprio 0
	s_barrier
	s_add_i32 s63, 0, 0x18000
	v_add_u32_e32 v136, s63, v182
	s_add_i32 s64, 0, 0x1c000
	ds_read_b128 v[166:169], v136
	ds_read_b128 v[170:173], v136 offset:1024
	ds_read_b128 v[186:189], v136 offset:2048
	ds_read_b128 v[190:193], v136 offset:3072
	v_add_u32_e32 v136, s64, v182
	ds_read_b128 v[194:197], v136
	ds_read_b128 v[198:201], v136 offset:1024
	ds_read_b128 v[202:205], v136 offset:2048
	ds_read_b128 v[210:213], v136 offset:3072
	s_add_u32 s42, s42, 0x40000
	s_addc_u32 s43, s43, 0
	s_mov_b32 m0, s48
	v_lshl_add_u64 v[250:251], s[42:43], 0, v[128:129]
	ds_read_b128 v[214:217], v185 offset:32768
	ds_read_b128 v[218:221], v185 offset:33792
	ds_read_b128 v[222:225], v185 offset:34816
	ds_read_b128 v[226:229], v185 offset:35840
	ds_read_b128 v[230:233], v185 offset:36864
	ds_read_b128 v[234:237], v185 offset:37888
	ds_read_b128 v[238:241], v185 offset:38912
	ds_read_b128 v[242:245], v185 offset:39936
	global_load_lds_dwordx4 v[250:251], off
	v_lshl_add_u64 v[250:251], s[42:43], 0, v[132:133]
	s_mov_b32 m0, s49
	s_nop 0
	global_load_lds_dwordx4 v[250:251], off
	s_waitcnt vmcnt(8)
	s_waitcnt lgkmcnt(0)
	s_barrier
	s_setprio 1
	s_waitcnt lgkmcnt(0)
	v_mfma_f32_16x16x32_bf16 v[124:127], v[166:169], v[214:217], v[124:127]
	v_mfma_f32_16x16x32_bf16 v[120:123], v[186:189], v[214:217], v[120:123]
	v_mfma_f32_16x16x32_bf16 v[108:111], v[166:169], v[222:225], v[108:111]
	v_mfma_f32_16x16x32_bf16 v[104:107], v[186:189], v[222:225], v[104:107]
	v_mfma_f32_16x16x32_bf16 v[92:95], v[166:169], v[230:233], v[92:95]
	v_mfma_f32_16x16x32_bf16 v[88:91], v[186:189], v[230:233], v[88:91]
	v_mfma_f32_16x16x32_bf16 v[76:79], v[166:169], v[238:241], v[76:79]
	v_mfma_f32_16x16x32_bf16 v[72:75], v[186:189], v[238:241], v[72:75]
	v_mfma_f32_16x16x32_bf16 v[124:127], v[170:173], v[218:221], v[124:127]
	v_mfma_f32_16x16x32_bf16 v[120:123], v[190:193], v[218:221], v[120:123]
	v_mfma_f32_16x16x32_bf16 v[108:111], v[170:173], v[226:229], v[108:111]
	v_mfma_f32_16x16x32_bf16 v[104:107], v[190:193], v[226:229], v[104:107]
	v_mfma_f32_16x16x32_bf16 v[92:95], v[170:173], v[234:237], v[92:95]
	v_mfma_f32_16x16x32_bf16 v[88:91], v[190:193], v[234:237], v[88:91]
	v_mfma_f32_16x16x32_bf16 v[76:79], v[170:173], v[242:245], v[76:79]
	v_mfma_f32_16x16x32_bf16 v[72:75], v[190:193], v[242:245], v[72:75]
	s_setprio 0
	s_setprio 1
	v_mfma_f32_16x16x32_bf16 v[116:119], v[194:197], v[214:217], v[116:119]
	v_mfma_f32_16x16x32_bf16 v[112:115], v[202:205], v[214:217], v[112:115]
	v_mfma_f32_16x16x32_bf16 v[100:103], v[194:197], v[222:225], v[100:103]
	v_mfma_f32_16x16x32_bf16 v[96:99], v[202:205], v[222:225], v[96:99]
	v_mfma_f32_16x16x32_bf16 v[84:87], v[194:197], v[230:233], v[84:87]
	v_mfma_f32_16x16x32_bf16 v[80:83], v[202:205], v[230:233], v[80:83]
	v_mfma_f32_16x16x32_bf16 v[68:71], v[194:197], v[238:241], v[68:71]
	v_mfma_f32_16x16x32_bf16 v[64:67], v[202:205], v[238:241], v[64:67]
	v_mfma_f32_16x16x32_bf16 v[116:119], v[198:201], v[218:221], v[116:119]
	v_mfma_f32_16x16x32_bf16 v[112:115], v[210:213], v[218:221], v[112:115]
	v_mfma_f32_16x16x32_bf16 v[100:103], v[198:201], v[226:229], v[100:103]
	v_mfma_f32_16x16x32_bf16 v[96:99], v[210:213], v[226:229], v[96:99]
	v_mfma_f32_16x16x32_bf16 v[84:87], v[198:201], v[234:237], v[84:87]
	v_mfma_f32_16x16x32_bf16 v[80:83], v[210:213], v[234:237], v[80:83]
	v_mfma_f32_16x16x32_bf16 v[68:71], v[198:201], v[242:245], v[68:71]
	v_mfma_f32_16x16x32_bf16 v[64:67], v[210:213], v[242:245], v[64:67]
	s_setprio 0
	s_barrier
	s_add_i32 s42, s63, s2
	v_lshl_add_u64 v[174:175], v[174:175], 0, s[18:19]
	s_mov_b32 m0, s42
	ds_read_b128 v[214:217], v185 offset:49152
	ds_read_b128 v[218:221], v185 offset:50176
	ds_read_b128 v[222:225], v185 offset:51200
	ds_read_b128 v[226:229], v185 offset:52224
	ds_read_b128 v[230:233], v185 offset:53248
	ds_read_b128 v[234:237], v185 offset:54272
	ds_read_b128 v[238:241], v185 offset:55296
	ds_read_b128 v[242:245], v185 offset:56320
	global_load_lds_dwordx4 v[174:175], off
	s_add_i32 m0, s42, 0x2000
	s_add_u32 s40, s40, 0x40080
	v_lshl_add_u64 v[174:175], v[206:207], 0, s[18:19]
	s_addc_u32 s41, s41, 0
	s_add_i32 s42, s64, s2
	global_load_lds_dwordx4 v[174:175], off
	v_lshl_add_u64 v[174:175], s[40:41], 0, v[130:131]
	s_mov_b32 m0, s42
	s_nop 0
	global_load_lds_dwordx4 v[174:175], off
	v_lshl_add_u64 v[174:175], s[40:41], 0, v[134:135]
	s_add_i32 m0, s42, 0x2000
	s_nop 0
	global_load_lds_dwordx4 v[174:175], off
	v_lshl_add_u64 v[174:175], v[246:247], 0, s[18:19]
	s_mov_b32 m0, s53
	s_nop 0
	global_load_lds_dwordx4 v[174:175], off
	v_lshl_add_u64 v[174:175], v[248:249], 0, s[18:19]
	s_mov_b32 m0, s54
	s_nop 0
	global_load_lds_dwordx4 v[174:175], off
	s_waitcnt vmcnt(8)
	s_waitcnt lgkmcnt(0)
	s_barrier
	s_setprio 1
	s_waitcnt lgkmcnt(0)
	v_mfma_f32_16x16x32_bf16 v[60:63], v[166:169], v[214:217], v[60:63]
	v_mfma_f32_16x16x32_bf16 v[56:59], v[186:189], v[214:217], v[56:59]
	v_mfma_f32_16x16x32_bf16 v[44:47], v[166:169], v[222:225], v[44:47]
	v_mfma_f32_16x16x32_bf16 v[40:43], v[186:189], v[222:225], v[40:43]
	v_mfma_f32_16x16x32_bf16 v[28:31], v[166:169], v[230:233], v[28:31]
	v_mfma_f32_16x16x32_bf16 v[24:27], v[186:189], v[230:233], v[24:27]
	v_mfma_f32_16x16x32_bf16 v[12:15], v[166:169], v[238:241], v[12:15]
	v_mfma_f32_16x16x32_bf16 v[8:11], v[186:189], v[238:241], v[8:11]
	v_mfma_f32_16x16x32_bf16 v[60:63], v[170:173], v[218:221], v[60:63]
	v_mfma_f32_16x16x32_bf16 v[56:59], v[190:193], v[218:221], v[56:59]
	v_mfma_f32_16x16x32_bf16 v[44:47], v[170:173], v[226:229], v[44:47]
	v_mfma_f32_16x16x32_bf16 v[40:43], v[190:193], v[226:229], v[40:43]
	v_mfma_f32_16x16x32_bf16 v[28:31], v[170:173], v[234:237], v[28:31]
	v_mfma_f32_16x16x32_bf16 v[24:27], v[190:193], v[234:237], v[24:27]
	v_mfma_f32_16x16x32_bf16 v[12:15], v[170:173], v[242:245], v[12:15]
	v_mfma_f32_16x16x32_bf16 v[8:11], v[190:193], v[242:245], v[8:11]
	s_setprio 0
	s_setprio 1
	v_mfma_f32_16x16x32_bf16 v[52:55], v[194:197], v[214:217], v[52:55]
	v_mfma_f32_16x16x32_bf16 v[48:51], v[202:205], v[214:217], v[48:51]
	v_mfma_f32_16x16x32_bf16 v[36:39], v[194:197], v[222:225], v[36:39]
	v_mfma_f32_16x16x32_bf16 v[32:35], v[202:205], v[222:225], v[32:35]
	v_mfma_f32_16x16x32_bf16 v[20:23], v[194:197], v[230:233], v[20:23]
	v_mfma_f32_16x16x32_bf16 v[16:19], v[202:205], v[230:233], v[16:19]
	v_mfma_f32_16x16x32_bf16 v[4:7], v[194:197], v[238:241], v[4:7]
	v_mfma_f32_16x16x32_bf16 v[0:3], v[202:205], v[238:241], v[0:3]
	v_mfma_f32_16x16x32_bf16 v[52:55], v[198:201], v[218:221], v[52:55]
	v_mfma_f32_16x16x32_bf16 v[48:51], v[210:213], v[218:221], v[48:51]
	v_mfma_f32_16x16x32_bf16 v[36:39], v[198:201], v[226:229], v[36:39]
	v_mfma_f32_16x16x32_bf16 v[32:35], v[210:213], v[226:229], v[32:35]
	v_mfma_f32_16x16x32_bf16 v[20:23], v[198:201], v[234:237], v[20:23]
	v_mfma_f32_16x16x32_bf16 v[16:19], v[210:213], v[234:237], v[16:19]
	v_mfma_f32_16x16x32_bf16 v[4:7], v[198:201], v[242:245], v[4:7]
	v_mfma_f32_16x16x32_bf16 v[0:3], v[210:213], v[242:245], v[0:3]
	s_setprio 0
	s_add_u32 s36, s36, 0x100
	s_addc_u32 s37, s37, 0
	s_add_u32 s30, s30, 0x100
	s_addc_u32 s31, s31, 0
	s_cmp_ge_u32 s62, s9
	s_mov_b32 s40, s62
	s_barrier
	s_cbranch_scc0 .LBB0_1493
	s_and_b64 vcc, exec, s[20:21]
	s_cbranch_vccz .LBB0_1496
	s_barrier

.LBB0_1695:
	ds_read_b128 v[154:157], v151
	ds_read_b128 v[158:161], v151 offset:1024
	ds_read_b128 v[162:165], v151 offset:2048
	ds_read_b128 v[166:169], v151 offset:3072
	ds_read_b128 v[170:173], v152
	ds_read_b128 v[182:185], v152 offset:1024
	ds_read_b128 v[186:189], v152 offset:2048
	ds_read_b128 v[190:193], v152 offset:3072
	s_add_u32 s40, s36, 0xfffc0080
	s_addc_u32 s41, s37, -1
	s_cmp_eq_u32 s65, 12
	s_cselect_b32 s43, s1, s41
	s_cselect_b32 s42, s0, s40
	s_cselect_b32 s41, s29, s64
	s_cselect_b32 s40, s28, s27
	v_lshl_add_u64 v[146:147], s[36:37], 0, v[138:139]
	s_add_i32 m0, s31, 0xc000
	ds_read_b128 v[194:197], v153
	ds_read_b128 v[198:201], v153 offset:1024
	ds_read_b128 v[202:205], v153 offset:2048
	ds_read_b128 v[210:213], v153 offset:3072
	ds_read_b128 v[214:217], v153 offset:4096
	ds_read_b128 v[218:221], v153 offset:5120
	ds_read_b128 v[222:225], v153 offset:6144
	ds_read_b128 v[226:229], v153 offset:7168
	global_load_lds_dwordx4 v[146:147], off
	v_lshl_add_u64 v[146:147], s[36:37], 0, v[140:141]
	s_add_i32 m0, s31, 0xe000
	s_nop 0
	global_load_lds_dwordx4 v[146:147], off
	s_waitcnt vmcnt(8)
	s_waitcnt lgkmcnt(0)
	s_barrier
	s_setprio 1
	s_waitcnt lgkmcnt(0)
	v_mfma_f32_16x16x32_bf16 v[124:127], v[154:157], v[194:197], v[124:127]
	v_mfma_f32_16x16x32_bf16 v[120:123], v[162:165], v[194:197], v[120:123]
	v_mfma_f32_16x16x32_bf16 v[108:111], v[154:157], v[202:205], v[108:111]
	v_mfma_f32_16x16x32_bf16 v[104:107], v[162:165], v[202:205], v[104:107]
	v_mfma_f32_16x16x32_bf16 v[92:95], v[154:157], v[214:217], v[92:95]
	v_mfma_f32_16x16x32_bf16 v[88:91], v[162:165], v[214:217], v[88:91]
	v_mfma_f32_16x16x32_bf16 v[76:79], v[154:157], v[222:225], v[76:79]
	v_mfma_f32_16x16x32_bf16 v[72:75], v[162:165], v[222:225], v[72:75]
	v_mfma_f32_16x16x32_bf16 v[124:127], v[158:161], v[198:201], v[124:127]
	v_mfma_f32_16x16x32_bf16 v[120:123], v[166:169], v[198:201], v[120:123]
	v_mfma_f32_16x16x32_bf16 v[108:111], v[158:161], v[210:213], v[108:111]
	v_mfma_f32_16x16x32_bf16 v[104:107], v[166:169], v[210:213], v[104:107]
	v_mfma_f32_16x16x32_bf16 v[92:95], v[158:161], v[218:221], v[92:95]
	v_mfma_f32_16x16x32_bf16 v[88:91], v[166:169], v[218:221], v[88:91]
	v_mfma_f32_16x16x32_bf16 v[76:79], v[158:161], v[226:229], v[76:79]
	v_mfma_f32_16x16x32_bf16 v[72:75], v[166:169], v[226:229], v[72:75]
	s_setprio 0
	s_setprio 1
	v_mfma_f32_16x16x32_bf16 v[116:119], v[170:173], v[194:197], v[116:119]
	v_mfma_f32_16x16x32_bf16 v[112:115], v[186:189], v[194:197], v[112:115]
	v_mfma_f32_16x16x32_bf16 v[100:103], v[170:173], v[202:205], v[100:103]
	v_mfma_f32_16x16x32_bf16 v[96:99], v[186:189], v[202:205], v[96:99]
	v_mfma_f32_16x16x32_bf16 v[84:87], v[170:173], v[214:217], v[84:87]
	v_mfma_f32_16x16x32_bf16 v[80:83], v[186:189], v[214:217], v[80:83]
	v_mfma_f32_16x16x32_bf16 v[68:71], v[170:173], v[222:225], v[68:71]
	v_mfma_f32_16x16x32_bf16 v[64:67], v[186:189], v[222:225], v[64:67]
	v_mfma_f32_16x16x32_bf16 v[116:119], v[182:185], v[198:201], v[116:119]
	v_mfma_f32_16x16x32_bf16 v[112:115], v[190:193], v[198:201], v[112:115]
	v_mfma_f32_16x16x32_bf16 v[100:103], v[182:185], v[210:213], v[100:103]
	v_mfma_f32_16x16x32_bf16 v[96:99], v[190:193], v[210:213], v[96:99]
	v_mfma_f32_16x16x32_bf16 v[84:87], v[182:185], v[218:221], v[84:87]
	v_mfma_f32_16x16x32_bf16 v[80:83], v[190:193], v[218:221], v[80:83]
	v_mfma_f32_16x16x32_bf16 v[68:71], v[182:185], v[226:229], v[68:71]
	v_mfma_f32_16x16x32_bf16 v[64:67], v[190:193], v[226:229], v[64:67]
	s_setprio 0
	s_barrier
	s_add_i32 s66, s53, s2
	v_lshl_add_u64 v[146:147], s[40:41], 0, v[132:133]
	s_mov_b32 m0, s66
	ds_read_b128 v[194:197], v153 offset:16384
	ds_read_b128 v[198:201], v153 offset:17408
	ds_read_b128 v[202:205], v153 offset:18432
	ds_read_b128 v[210:213], v153 offset:19456
	ds_read_b128 v[214:217], v153 offset:20480
	ds_read_b128 v[218:221], v153 offset:21504
	ds_read_b128 v[222:225], v153 offset:22528
	ds_read_b128 v[226:229], v153 offset:23552
	global_load_lds_dwordx4 v[146:147], off
	s_add_i32 m0, s66, 0x2000
	s_add_u32 s66, s40, 0x40000
	v_lshl_add_u64 v[174:175], s[40:41], 0, v[128:129]
	s_addc_u32 s67, s41, 0
	s_add_i32 s68, s54, s2
	global_load_lds_dwordx4 v[174:175], off
	v_lshl_add_u64 v[206:207], s[66:67], 0, v[132:133]
	s_mov_b32 m0, s68
	v_lshl_add_u64 v[230:231], s[42:43], 0, v[130:131]
	global_load_lds_dwordx4 v[206:207], off
	v_lshl_add_u64 v[206:207], s[66:67], 0, v[128:129]
	s_add_i32 m0, s68, 0x2000
	s_nop 0
	global_load_lds_dwordx4 v[206:207], off
	v_lshl_add_u64 v[206:207], s[42:43], 0, v[134:135]
	s_mov_b32 m0, s31
	s_nop 0
	global_load_lds_dwordx4 v[206:207], off
	s_mov_b32 m0, s35
	s_nop 0
	global_load_lds_dwordx4 v[230:231], off
	s_waitcnt vmcnt(8)
	s_waitcnt lgkmcnt(0)
	s_barrier
	s_setprio 1
	s_waitcnt lgkmcnt(0)
	v_mfma_f32_16x16x32_bf16 v[60:63], v[154:157], v[194:197], v[60:63]
	v_mfma_f32_16x16x32_bf16 v[56:59], v[162:165], v[194:197], v[56:59]
	v_mfma_f32_16x16x32_bf16 v[44:47], v[154:157], v[202:205], v[44:47]
	v_mfma_f32_16x16x32_bf16 v[40:43], v[162:165], v[202:205], v[40:43]
	v_mfma_f32_16x16x32_bf16 v[28:31], v[154:157], v[214:217], v[28:31]
	v_mfma_f32_16x16x32_bf16 v[24:27], v[162:165], v[214:217], v[24:27]
	v_mfma_f32_16x16x32_bf16 v[12:15], v[154:157], v[222:225], v[12:15]
	v_mfma_f32_16x16x32_bf16 v[8:11], v[162:165], v[222:225], v[8:11]
	v_mfma_f32_16x16x32_bf16 v[60:63], v[158:161], v[198:201], v[60:63]
	v_mfma_f32_16x16x32_bf16 v[56:59], v[166:169], v[198:201], v[56:59]
	v_mfma_f32_16x16x32_bf16 v[44:47], v[158:161], v[210:213], v[44:47]
	v_mfma_f32_16x16x32_bf16 v[40:43], v[166:169], v[210:213], v[40:43]
	v_mfma_f32_16x16x32_bf16 v[28:31], v[158:161], v[218:221], v[28:31]
	v_mfma_f32_16x16x32_bf16 v[24:27], v[166:169], v[218:221], v[24:27]
	v_mfma_f32_16x16x32_bf16 v[12:15], v[158:161], v[226:229], v[12:15]
	v_mfma_f32_16x16x32_bf16 v[8:11], v[166:169], v[226:229], v[8:11]
	s_setprio 0
	s_setprio 1
	v_mfma_f32_16x16x32_bf16 v[52:55], v[170:173], v[194:197], v[52:55]
	v_mfma_f32_16x16x32_bf16 v[48:51], v[186:189], v[194:197], v[48:51]
	v_mfma_f32_16x16x32_bf16 v[36:39], v[170:173], v[202:205], v[36:39]
	v_mfma_f32_16x16x32_bf16 v[32:35], v[186:189], v[202:205], v[32:35]
	v_mfma_f32_16x16x32_bf16 v[20:23], v[170:173], v[214:217], v[20:23]
	v_mfma_f32_16x16x32_bf16 v[16:19], v[186:189], v[214:217], v[16:19]
	v_mfma_f32_16x16x32_bf16 v[4:7], v[170:173], v[222:225], v[4:7]
	v_mfma_f32_16x16x32_bf16 v[0:3], v[186:189], v[222:225], v[0:3]
	v_mfma_f32_16x16x32_bf16 v[52:55], v[182:185], v[198:201], v[52:55]
	v_mfma_f32_16x16x32_bf16 v[48:51], v[190:193], v[198:201], v[48:51]
	v_mfma_f32_16x16x32_bf16 v[36:39], v[182:185], v[210:213], v[36:39]
	v_mfma_f32_16x16x32_bf16 v[32:35], v[190:193], v[210:213], v[32:35]
	v_mfma_f32_16x16x32_bf16 v[20:23], v[182:185], v[218:221], v[20:23]
	v_mfma_f32_16x16x32_bf16 v[16:19], v[190:193], v[218:221], v[16:19]
	v_mfma_f32_16x16x32_bf16 v[4:7], v[182:185], v[226:229], v[4:7]
	v_mfma_f32_16x16x32_bf16 v[0:3], v[190:193], v[226:229], v[0:3]
	s_setprio 0
	s_barrier
	s_add_i32 s66, 0, 0x18000
	v_add_u32_e32 v136, s66, v149
	s_add_i32 s67, 0, 0x1c000
	ds_read_b128 v[154:157], v136
	ds_read_b128 v[158:161], v136 offset:1024
	ds_read_b128 v[162:165], v136 offset:2048
	ds_read_b128 v[166:169], v136 offset:3072
	v_add_u32_e32 v136, s67, v149
	ds_read_b128 v[170:173], v136
	ds_read_b128 v[182:185], v136 offset:1024
	ds_read_b128 v[186:189], v136 offset:2048
	ds_read_b128 v[190:193], v136 offset:3072
	s_add_u32 s42, s42, 0x40000
	s_addc_u32 s43, s43, 0
	s_mov_b32 m0, s44
	v_lshl_add_u64 v[232:233], s[42:43], 0, v[134:135]
	ds_read_b128 v[194:197], v153 offset:32768
	ds_read_b128 v[198:201], v153 offset:33792
	ds_read_b128 v[202:205], v153 offset:34816
	ds_read_b128 v[210:213], v153 offset:35840
	ds_read_b128 v[214:217], v153 offset:36864
	ds_read_b128 v[218:221], v153 offset:37888
	ds_read_b128 v[222:225], v153 offset:38912
	ds_read_b128 v[226:229], v153 offset:39936
	global_load_lds_dwordx4 v[232:233], off
	v_lshl_add_u64 v[232:233], s[42:43], 0, v[130:131]
	s_mov_b32 m0, s45
	s_nop 0
	global_load_lds_dwordx4 v[232:233], off
	s_waitcnt vmcnt(8)
	s_waitcnt lgkmcnt(0)
	s_barrier
	s_setprio 1
	s_waitcnt lgkmcnt(0)
	v_mfma_f32_16x16x32_bf16 v[124:127], v[154:157], v[194:197], v[124:127]
	v_mfma_f32_16x16x32_bf16 v[120:123], v[162:165], v[194:197], v[120:123]
	v_mfma_f32_16x16x32_bf16 v[108:111], v[154:157], v[202:205], v[108:111]
	v_mfma_f32_16x16x32_bf16 v[104:107], v[162:165], v[202:205], v[104:107]
	v_mfma_f32_16x16x32_bf16 v[92:95], v[154:157], v[214:217], v[92:95]
	v_mfma_f32_16x16x32_bf16 v[88:91], v[162:165], v[214:217], v[88:91]
	v_mfma_f32_16x16x32_bf16 v[76:79], v[154:157], v[222:225], v[76:79]
	v_mfma_f32_16x16x32_bf16 v[72:75], v[162:165], v[222:225], v[72:75]
	v_mfma_f32_16x16x32_bf16 v[124:127], v[158:161], v[198:201], v[124:127]
	v_mfma_f32_16x16x32_bf16 v[120:123], v[166:169], v[198:201], v[120:123]
	v_mfma_f32_16x16x32_bf16 v[108:111], v[158:161], v[210:213], v[108:111]
	v_mfma_f32_16x16x32_bf16 v[104:107], v[166:169], v[210:213], v[104:107]
	v_mfma_f32_16x16x32_bf16 v[92:95], v[158:161], v[218:221], v[92:95]
	v_mfma_f32_16x16x32_bf16 v[88:91], v[166:169], v[218:221], v[88:91]
	v_mfma_f32_16x16x32_bf16 v[76:79], v[158:161], v[226:229], v[76:79]
	v_mfma_f32_16x16x32_bf16 v[72:75], v[166:169], v[226:229], v[72:75]
	s_setprio 0
	s_setprio 1
	v_mfma_f32_16x16x32_bf16 v[116:119], v[170:173], v[194:197], v[116:119]
	v_mfma_f32_16x16x32_bf16 v[112:115], v[186:189], v[194:197], v[112:115]
	v_mfma_f32_16x16x32_bf16 v[100:103], v[170:173], v[202:205], v[100:103]
	v_mfma_f32_16x16x32_bf16 v[96:99], v[186:189], v[202:205], v[96:99]
	v_mfma_f32_16x16x32_bf16 v[84:87], v[170:173], v[214:217], v[84:87]
	v_mfma_f32_16x16x32_bf16 v[80:83], v[186:189], v[214:217], v[80:83]
	v_mfma_f32_16x16x32_bf16 v[68:71], v[170:173], v[222:225], v[68:71]
	v_mfma_f32_16x16x32_bf16 v[64:67], v[186:189], v[222:225], v[64:67]
	v_mfma_f32_16x16x32_bf16 v[116:119], v[182:185], v[198:201], v[116:119]
	v_mfma_f32_16x16x32_bf16 v[112:115], v[190:193], v[198:201], v[112:115]
	v_mfma_f32_16x16x32_bf16 v[100:103], v[182:185], v[210:213], v[100:103]
	v_mfma_f32_16x16x32_bf16 v[96:99], v[190:193], v[210:213], v[96:99]
	v_mfma_f32_16x16x32_bf16 v[84:87], v[182:185], v[218:221], v[84:87]
	v_mfma_f32_16x16x32_bf16 v[80:83], v[190:193], v[218:221], v[80:83]
	v_mfma_f32_16x16x32_bf16 v[68:71], v[182:185], v[226:229], v[68:71]
	v_mfma_f32_16x16x32_bf16 v[64:67], v[190:193], v[226:229], v[64:67]
	s_setprio 0
	s_barrier
	s_add_i32 s42, s66, s2
	v_lshl_add_u64 v[146:147], v[146:147], 0, s[14:15]
	s_mov_b32 m0, s42
	ds_read_b128 v[194:197], v153 offset:49152
	ds_read_b128 v[198:201], v153 offset:50176
	ds_read_b128 v[202:205], v153 offset:51200
	ds_read_b128 v[210:213], v153 offset:52224
	ds_read_b128 v[214:217], v153 offset:53248
	ds_read_b128 v[218:221], v153 offset:54272
	ds_read_b128 v[222:225], v153 offset:55296
	ds_read_b128 v[226:229], v153 offset:56320
	global_load_lds_dwordx4 v[146:147], off
	s_add_i32 m0, s42, 0x2000
	s_add_u32 s40, s40, 0x40080
	v_lshl_add_u64 v[146:147], v[174:175], 0, s[14:15]
	s_addc_u32 s41, s41, 0
	s_add_i32 s42, s67, s2
	global_load_lds_dwordx4 v[146:147], off
	v_lshl_add_u64 v[146:147], s[40:41], 0, v[132:133]
	s_mov_b32 m0, s42
	s_nop 0
	global_load_lds_dwordx4 v[146:147], off
	v_lshl_add_u64 v[146:147], s[40:41], 0, v[128:129]
	s_add_i32 m0, s42, 0x2000
	s_nop 0
	global_load_lds_dwordx4 v[146:147], off
	v_lshl_add_u64 v[146:147], v[206:207], 0, s[14:15]
	s_mov_b32 m0, s49
	s_nop 0
	global_load_lds_dwordx4 v[146:147], off
	v_lshl_add_u64 v[146:147], v[230:231], 0, s[14:15]
	s_mov_b32 m0, s52
	s_nop 0
	global_load_lds_dwordx4 v[146:147], off
	s_waitcnt vmcnt(8)
	s_waitcnt lgkmcnt(0)
	s_barrier
	s_setprio 1
	s_waitcnt lgkmcnt(0)
	v_mfma_f32_16x16x32_bf16 v[60:63], v[154:157], v[194:197], v[60:63]
	v_mfma_f32_16x16x32_bf16 v[56:59], v[162:165], v[194:197], v[56:59]
	v_mfma_f32_16x16x32_bf16 v[44:47], v[154:157], v[202:205], v[44:47]
	v_mfma_f32_16x16x32_bf16 v[40:43], v[162:165], v[202:205], v[40:43]
	v_mfma_f32_16x16x32_bf16 v[28:31], v[154:157], v[214:217], v[28:31]
	v_mfma_f32_16x16x32_bf16 v[24:27], v[162:165], v[214:217], v[24:27]
	v_mfma_f32_16x16x32_bf16 v[12:15], v[154:157], v[222:225], v[12:15]
	v_mfma_f32_16x16x32_bf16 v[8:11], v[162:165], v[222:225], v[8:11]
	v_mfma_f32_16x16x32_bf16 v[60:63], v[158:161], v[198:201], v[60:63]
	v_mfma_f32_16x16x32_bf16 v[56:59], v[166:169], v[198:201], v[56:59]
	v_mfma_f32_16x16x32_bf16 v[44:47], v[158:161], v[210:213], v[44:47]
	v_mfma_f32_16x16x32_bf16 v[40:43], v[166:169], v[210:213], v[40:43]
	v_mfma_f32_16x16x32_bf16 v[28:31], v[158:161], v[218:221], v[28:31]
	v_mfma_f32_16x16x32_bf16 v[24:27], v[166:169], v[218:221], v[24:27]
	v_mfma_f32_16x16x32_bf16 v[12:15], v[158:161], v[226:229], v[12:15]
	v_mfma_f32_16x16x32_bf16 v[8:11], v[166:169], v[226:229], v[8:11]
	s_setprio 0
	s_setprio 1
	v_mfma_f32_16x16x32_bf16 v[52:55], v[170:173], v[194:197], v[52:55]
	v_mfma_f32_16x16x32_bf16 v[48:51], v[186:189], v[194:197], v[48:51]
	v_mfma_f32_16x16x32_bf16 v[36:39], v[170:173], v[202:205], v[36:39]
	v_mfma_f32_16x16x32_bf16 v[32:35], v[186:189], v[202:205], v[32:35]
	v_mfma_f32_16x16x32_bf16 v[20:23], v[170:173], v[214:217], v[20:23]
	v_mfma_f32_16x16x32_bf16 v[16:19], v[186:189], v[214:217], v[16:19]
	v_mfma_f32_16x16x32_bf16 v[4:7], v[170:173], v[222:225], v[4:7]
	v_mfma_f32_16x16x32_bf16 v[0:3], v[186:189], v[222:225], v[0:3]
	v_mfma_f32_16x16x32_bf16 v[52:55], v[182:185], v[198:201], v[52:55]
	v_mfma_f32_16x16x32_bf16 v[48:51], v[190:193], v[198:201], v[48:51]
	v_mfma_f32_16x16x32_bf16 v[36:39], v[182:185], v[210:213], v[36:39]
	v_mfma_f32_16x16x32_bf16 v[32:35], v[190:193], v[210:213], v[32:35]
	v_mfma_f32_16x16x32_bf16 v[20:23], v[182:185], v[218:221], v[20:23]
	v_mfma_f32_16x16x32_bf16 v[16:19], v[190:193], v[218:221], v[16:19]
	v_mfma_f32_16x16x32_bf16 v[4:7], v[182:185], v[226:229], v[4:7]
	v_mfma_f32_16x16x32_bf16 v[0:3], v[190:193], v[226:229], v[0:3]
	s_setprio 0
	s_add_i32 s65, s65, 2
	s_add_u32 s36, s36, 0x100
	s_addc_u32 s37, s37, 0
	s_add_u32 s27, s27, 0x100
	s_addc_u32 s64, s64, 0
	s_cmp_gt_u32 s65, 13
	s_barrier
	s_cbranch_scc0 .LBB0_1695
	s_and_b64 vcc, exec, s[16:17]
	s_cbranch_vccz .LBB0_1698
	s_barrier

.LBB0_1791:
	ds_read_b128 v[166:169], v183
	ds_read_b128 v[170:173], v183 offset:1024
	ds_read_b128 v[186:189], v183 offset:2048
	ds_read_b128 v[190:193], v183 offset:3072
	ds_read_b128 v[194:197], v184
	ds_read_b128 v[198:201], v184 offset:1024
	ds_read_b128 v[202:205], v184 offset:2048
	ds_read_b128 v[210:213], v184 offset:3072
	s_add_i32 s57, s36, 2
	s_add_u32 s37, s4, 0xfff00080
	s_addc_u32 s40, s5, -1
	s_cmp_eq_u32 s27, s36
	s_cselect_b32 s36, s34, s30
	s_cselect_b32 s41, s1, s40
	s_cselect_b32 s40, s0, s37
	s_cselect_b32 s37, s35, s31
	v_lshl_add_u64 v[174:175], s[4:5], 0, v[156:157]
	s_add_i32 m0, s42, 0xc000
	ds_read_b128 v[214:217], v185
	ds_read_b128 v[218:221], v185 offset:1024
	ds_read_b128 v[222:225], v185 offset:2048
	ds_read_b128 v[226:229], v185 offset:3072
	ds_read_b128 v[230:233], v185 offset:4096
	ds_read_b128 v[234:237], v185 offset:5120
	ds_read_b128 v[238:241], v185 offset:6144
	ds_read_b128 v[242:245], v185 offset:7168
	global_load_lds_dwordx4 v[174:175], off
	v_lshl_add_u64 v[174:175], s[4:5], 0, v[158:159]
	s_add_i32 m0, s42, 0xe000
	s_nop 0
	global_load_lds_dwordx4 v[174:175], off
	s_waitcnt vmcnt(8)
	s_waitcnt lgkmcnt(0)
	s_barrier
	s_setprio 1
	s_waitcnt lgkmcnt(0)
	v_mfma_f32_16x16x32_bf16 v[124:127], v[166:169], v[214:217], v[124:127]
	v_mfma_f32_16x16x32_bf16 v[120:123], v[186:189], v[214:217], v[120:123]
	v_mfma_f32_16x16x32_bf16 v[108:111], v[166:169], v[222:225], v[108:111]
	v_mfma_f32_16x16x32_bf16 v[104:107], v[186:189], v[222:225], v[104:107]
	v_mfma_f32_16x16x32_bf16 v[92:95], v[166:169], v[230:233], v[92:95]
	v_mfma_f32_16x16x32_bf16 v[88:91], v[186:189], v[230:233], v[88:91]
	v_mfma_f32_16x16x32_bf16 v[76:79], v[166:169], v[238:241], v[76:79]
	v_mfma_f32_16x16x32_bf16 v[72:75], v[186:189], v[238:241], v[72:75]
	v_mfma_f32_16x16x32_bf16 v[124:127], v[170:173], v[218:221], v[124:127]
	v_mfma_f32_16x16x32_bf16 v[120:123], v[190:193], v[218:221], v[120:123]
	v_mfma_f32_16x16x32_bf16 v[108:111], v[170:173], v[226:229], v[108:111]
	v_mfma_f32_16x16x32_bf16 v[104:107], v[190:193], v[226:229], v[104:107]
	v_mfma_f32_16x16x32_bf16 v[92:95], v[170:173], v[234:237], v[92:95]
	v_mfma_f32_16x16x32_bf16 v[88:91], v[190:193], v[234:237], v[88:91]
	v_mfma_f32_16x16x32_bf16 v[76:79], v[170:173], v[242:245], v[76:79]
	v_mfma_f32_16x16x32_bf16 v[72:75], v[190:193], v[242:245], v[72:75]
	s_setprio 0
	s_setprio 1
	v_mfma_f32_16x16x32_bf16 v[116:119], v[194:197], v[214:217], v[116:119]
	v_mfma_f32_16x16x32_bf16 v[112:115], v[202:205], v[214:217], v[112:115]
	v_mfma_f32_16x16x32_bf16 v[100:103], v[194:197], v[222:225], v[100:103]
	v_mfma_f32_16x16x32_bf16 v[96:99], v[202:205], v[222:225], v[96:99]
	v_mfma_f32_16x16x32_bf16 v[84:87], v[194:197], v[230:233], v[84:87]
	v_mfma_f32_16x16x32_bf16 v[80:83], v[202:205], v[230:233], v[80:83]
	v_mfma_f32_16x16x32_bf16 v[68:71], v[194:197], v[238:241], v[68:71]
	v_mfma_f32_16x16x32_bf16 v[64:67], v[202:205], v[238:241], v[64:67]
	v_mfma_f32_16x16x32_bf16 v[116:119], v[198:201], v[218:221], v[116:119]
	v_mfma_f32_16x16x32_bf16 v[112:115], v[210:213], v[218:221], v[112:115]
	v_mfma_f32_16x16x32_bf16 v[100:103], v[198:201], v[226:229], v[100:103]
	v_mfma_f32_16x16x32_bf16 v[96:99], v[210:213], v[226:229], v[96:99]
	v_mfma_f32_16x16x32_bf16 v[84:87], v[198:201], v[234:237], v[84:87]
	v_mfma_f32_16x16x32_bf16 v[80:83], v[210:213], v[234:237], v[80:83]
	v_mfma_f32_16x16x32_bf16 v[68:71], v[198:201], v[242:245], v[68:71]
	v_mfma_f32_16x16x32_bf16 v[64:67], v[210:213], v[242:245], v[64:67]
	s_setprio 0
	s_barrier
	s_add_i32 s61, s53, s2
	v_lshl_add_u64 v[174:175], s[36:37], 0, v[130:131]
	s_mov_b32 m0, s61
	ds_read_b128 v[214:217], v185 offset:16384
	ds_read_b128 v[218:221], v185 offset:17408
	ds_read_b128 v[222:225], v185 offset:18432
	ds_read_b128 v[226:229], v185 offset:19456
	ds_read_b128 v[230:233], v185 offset:20480
	ds_read_b128 v[234:237], v185 offset:21504
	ds_read_b128 v[238:241], v185 offset:22528
	ds_read_b128 v[242:245], v185 offset:23552
	global_load_lds_dwordx4 v[174:175], off
	s_add_i32 m0, s61, 0x2000
	s_add_u32 s62, s36, 0x100000
	v_lshl_add_u64 v[206:207], s[36:37], 0, v[134:135]
	s_addc_u32 s63, s37, 0
	s_add_i32 s61, s54, s2
	global_load_lds_dwordx4 v[206:207], off
	v_lshl_add_u64 v[246:247], s[62:63], 0, v[130:131]
	s_mov_b32 m0, s61
	v_lshl_add_u64 v[248:249], s[40:41], 0, v[132:133]
	global_load_lds_dwordx4 v[246:247], off
	v_lshl_add_u64 v[246:247], s[62:63], 0, v[134:135]
	s_add_i32 m0, s61, 0x2000
	s_nop 0
	global_load_lds_dwordx4 v[246:247], off
	v_lshl_add_u64 v[246:247], s[40:41], 0, v[128:129]
	s_mov_b32 m0, s42
	s_nop 0
	global_load_lds_dwordx4 v[246:247], off
	s_mov_b32 m0, s43
	s_nop 0
	global_load_lds_dwordx4 v[248:249], off
	s_waitcnt vmcnt(8)
	s_waitcnt lgkmcnt(0)
	s_barrier
	s_setprio 1
	s_waitcnt lgkmcnt(0)
	v_mfma_f32_16x16x32_bf16 v[60:63], v[166:169], v[214:217], v[60:63]
	v_mfma_f32_16x16x32_bf16 v[56:59], v[186:189], v[214:217], v[56:59]
	v_mfma_f32_16x16x32_bf16 v[44:47], v[166:169], v[222:225], v[44:47]
	v_mfma_f32_16x16x32_bf16 v[40:43], v[186:189], v[222:225], v[40:43]
	v_mfma_f32_16x16x32_bf16 v[28:31], v[166:169], v[230:233], v[28:31]
	v_mfma_f32_16x16x32_bf16 v[24:27], v[186:189], v[230:233], v[24:27]
	v_mfma_f32_16x16x32_bf16 v[12:15], v[166:169], v[238:241], v[12:15]
	v_mfma_f32_16x16x32_bf16 v[8:11], v[186:189], v[238:241], v[8:11]
	v_mfma_f32_16x16x32_bf16 v[60:63], v[170:173], v[218:221], v[60:63]
	v_mfma_f32_16x16x32_bf16 v[56:59], v[190:193], v[218:221], v[56:59]
	v_mfma_f32_16x16x32_bf16 v[44:47], v[170:173], v[226:229], v[44:47]
	v_mfma_f32_16x16x32_bf16 v[40:43], v[190:193], v[226:229], v[40:43]
	v_mfma_f32_16x16x32_bf16 v[28:31], v[170:173], v[234:237], v[28:31]
	v_mfma_f32_16x16x32_bf16 v[24:27], v[190:193], v[234:237], v[24:27]
	v_mfma_f32_16x16x32_bf16 v[12:15], v[170:173], v[242:245], v[12:15]
	v_mfma_f32_16x16x32_bf16 v[8:11], v[190:193], v[242:245], v[8:11]
	s_setprio 0
	s_setprio 1
	v_mfma_f32_16x16x32_bf16 v[52:55], v[194:197], v[214:217], v[52:55]
	v_mfma_f32_16x16x32_bf16 v[48:51], v[202:205], v[214:217], v[48:51]
	v_mfma_f32_16x16x32_bf16 v[36:39], v[194:197], v[222:225], v[36:39]
	v_mfma_f32_16x16x32_bf16 v[32:35], v[202:205], v[222:225], v[32:35]
	v_mfma_f32_16x16x32_bf16 v[20:23], v[194:197], v[230:233], v[20:23]
	v_mfma_f32_16x16x32_bf16 v[16:19], v[202:205], v[230:233], v[16:19]
	v_mfma_f32_16x16x32_bf16 v[4:7], v[194:197], v[238:241], v[4:7]
	v_mfma_f32_16x16x32_bf16 v[0:3], v[202:205], v[238:241], v[0:3]
	v_mfma_f32_16x16x32_bf16 v[52:55], v[198:201], v[218:221], v[52:55]
	v_mfma_f32_16x16x32_bf16 v[48:51], v[210:213], v[218:221], v[48:51]
	v_mfma_f32_16x16x32_bf16 v[36:39], v[198:201], v[226:229], v[36:39]
	v_mfma_f32_16x16x32_bf16 v[32:35], v[210:213], v[226:229], v[32:35]
	v_mfma_f32_16x16x32_bf16 v[20:23], v[198:201], v[234:237], v[20:23]
	v_mfma_f32_16x16x32_bf16 v[16:19], v[210:213], v[234:237], v[16:19]
	v_mfma_f32_16x16x32_bf16 v[4:7], v[198:201], v[242:245], v[4:7]
	v_mfma_f32_16x16x32_bf16 v[0:3], v[210:213], v[242:245], v[0:3]
	s_setprio 0
	s_barrier
	s_add_i32 s61, 0, 0x18000
	v_add_u32_e32 v136, s61, v182
	s_add_i32 s62, 0, 0x1c000
	ds_read_b128 v[166:169], v136
	ds_read_b128 v[170:173], v136 offset:1024
	ds_read_b128 v[186:189], v136 offset:2048
	ds_read_b128 v[190:193], v136 offset:3072
	v_add_u32_e32 v136, s62, v182
	ds_read_b128 v[194:197], v136
	ds_read_b128 v[198:201], v136 offset:1024
	ds_read_b128 v[202:205], v136 offset:2048
	ds_read_b128 v[210:213], v136 offset:3072
	s_add_u32 s40, s40, 0x100000
	s_addc_u32 s41, s41, 0
	s_mov_b32 m0, s44
	v_lshl_add_u64 v[250:251], s[40:41], 0, v[128:129]
	ds_read_b128 v[214:217], v185 offset:32768
	ds_read_b128 v[218:221], v185 offset:33792
	ds_read_b128 v[222:225], v185 offset:34816
	ds_read_b128 v[226:229], v185 offset:35840
	ds_read_b128 v[230:233], v185 offset:36864
	ds_read_b128 v[234:237], v185 offset:37888
	ds_read_b128 v[238:241], v185 offset:38912
	ds_read_b128 v[242:245], v185 offset:39936
	global_load_lds_dwordx4 v[250:251], off
	v_lshl_add_u64 v[250:251], s[40:41], 0, v[132:133]
	s_mov_b32 m0, s45
	s_nop 0
	global_load_lds_dwordx4 v[250:251], off
	s_waitcnt vmcnt(8)
	s_waitcnt lgkmcnt(0)
	s_barrier
	s_setprio 1
	s_waitcnt lgkmcnt(0)
	v_mfma_f32_16x16x32_bf16 v[124:127], v[166:169], v[214:217], v[124:127]
	v_mfma_f32_16x16x32_bf16 v[120:123], v[186:189], v[214:217], v[120:123]
	v_mfma_f32_16x16x32_bf16 v[108:111], v[166:169], v[222:225], v[108:111]
	v_mfma_f32_16x16x32_bf16 v[104:107], v[186:189], v[222:225], v[104:107]
	v_mfma_f32_16x16x32_bf16 v[92:95], v[166:169], v[230:233], v[92:95]
	v_mfma_f32_16x16x32_bf16 v[88:91], v[186:189], v[230:233], v[88:91]
	v_mfma_f32_16x16x32_bf16 v[76:79], v[166:169], v[238:241], v[76:79]
	v_mfma_f32_16x16x32_bf16 v[72:75], v[186:189], v[238:241], v[72:75]
	v_mfma_f32_16x16x32_bf16 v[124:127], v[170:173], v[218:221], v[124:127]
	v_mfma_f32_16x16x32_bf16 v[120:123], v[190:193], v[218:221], v[120:123]
	v_mfma_f32_16x16x32_bf16 v[108:111], v[170:173], v[226:229], v[108:111]
	v_mfma_f32_16x16x32_bf16 v[104:107], v[190:193], v[226:229], v[104:107]
	v_mfma_f32_16x16x32_bf16 v[92:95], v[170:173], v[234:237], v[92:95]
	v_mfma_f32_16x16x32_bf16 v[88:91], v[190:193], v[234:237], v[88:91]
	v_mfma_f32_16x16x32_bf16 v[76:79], v[170:173], v[242:245], v[76:79]
	v_mfma_f32_16x16x32_bf16 v[72:75], v[190:193], v[242:245], v[72:75]
	s_setprio 0
	s_setprio 1
	v_mfma_f32_16x16x32_bf16 v[116:119], v[194:197], v[214:217], v[116:119]
	v_mfma_f32_16x16x32_bf16 v[112:115], v[202:205], v[214:217], v[112:115]
	v_mfma_f32_16x16x32_bf16 v[100:103], v[194:197], v[222:225], v[100:103]
	v_mfma_f32_16x16x32_bf16 v[96:99], v[202:205], v[222:225], v[96:99]
	v_mfma_f32_16x16x32_bf16 v[84:87], v[194:197], v[230:233], v[84:87]
	v_mfma_f32_16x16x32_bf16 v[80:83], v[202:205], v[230:233], v[80:83]
	v_mfma_f32_16x16x32_bf16 v[68:71], v[194:197], v[238:241], v[68:71]
	v_mfma_f32_16x16x32_bf16 v[64:67], v[202:205], v[238:241], v[64:67]
	v_mfma_f32_16x16x32_bf16 v[116:119], v[198:201], v[218:221], v[116:119]
	v_mfma_f32_16x16x32_bf16 v[112:115], v[210:213], v[218:221], v[112:115]
	v_mfma_f32_16x16x32_bf16 v[100:103], v[198:201], v[226:229], v[100:103]
	v_mfma_f32_16x16x32_bf16 v[96:99], v[210:213], v[226:229], v[96:99]
	v_mfma_f32_16x16x32_bf16 v[84:87], v[198:201], v[234:237], v[84:87]
	v_mfma_f32_16x16x32_bf16 v[80:83], v[210:213], v[234:237], v[80:83]
	v_mfma_f32_16x16x32_bf16 v[68:71], v[198:201], v[242:245], v[68:71]
	v_mfma_f32_16x16x32_bf16 v[64:67], v[210:213], v[242:245], v[64:67]
	s_setprio 0
	s_barrier
	s_add_i32 s40, s61, s2
	v_lshl_add_u64 v[174:175], v[174:175], 0, s[14:15]
	s_mov_b32 m0, s40
	ds_read_b128 v[214:217], v185 offset:49152
	ds_read_b128 v[218:221], v185 offset:50176
	ds_read_b128 v[222:225], v185 offset:51200
	ds_read_b128 v[226:229], v185 offset:52224
	ds_read_b128 v[230:233], v185 offset:53248
	ds_read_b128 v[234:237], v185 offset:54272
	ds_read_b128 v[238:241], v185 offset:55296
	ds_read_b128 v[242:245], v185 offset:56320
	global_load_lds_dwordx4 v[174:175], off
	s_add_i32 m0, s40, 0x2000
	s_add_u32 s36, s36, 0x100080
	v_lshl_add_u64 v[174:175], v[206:207], 0, s[14:15]
	s_addc_u32 s37, s37, 0
	s_add_i32 s40, s62, s2
	global_load_lds_dwordx4 v[174:175], off
	v_lshl_add_u64 v[174:175], s[36:37], 0, v[130:131]
	s_mov_b32 m0, s40
	s_nop 0
	global_load_lds_dwordx4 v[174:175], off
	v_lshl_add_u64 v[174:175], s[36:37], 0, v[134:135]
	s_add_i32 m0, s40, 0x2000
	s_nop 0
	global_load_lds_dwordx4 v[174:175], off
	v_lshl_add_u64 v[174:175], v[246:247], 0, s[14:15]
	s_mov_b32 m0, s49
	s_nop 0
	global_load_lds_dwordx4 v[174:175], off
	v_lshl_add_u64 v[174:175], v[248:249], 0, s[14:15]
	s_mov_b32 m0, s52
	s_nop 0
	global_load_lds_dwordx4 v[174:175], off
	s_waitcnt vmcnt(8)
	s_waitcnt lgkmcnt(0)
	s_barrier
	s_setprio 1
	s_waitcnt lgkmcnt(0)
	v_mfma_f32_16x16x32_bf16 v[60:63], v[166:169], v[214:217], v[60:63]
	v_mfma_f32_16x16x32_bf16 v[56:59], v[186:189], v[214:217], v[56:59]
	v_mfma_f32_16x16x32_bf16 v[44:47], v[166:169], v[222:225], v[44:47]
	v_mfma_f32_16x16x32_bf16 v[40:43], v[186:189], v[222:225], v[40:43]
	v_mfma_f32_16x16x32_bf16 v[28:31], v[166:169], v[230:233], v[28:31]
	v_mfma_f32_16x16x32_bf16 v[24:27], v[186:189], v[230:233], v[24:27]
	v_mfma_f32_16x16x32_bf16 v[12:15], v[166:169], v[238:241], v[12:15]
	v_mfma_f32_16x16x32_bf16 v[8:11], v[186:189], v[238:241], v[8:11]
	v_mfma_f32_16x16x32_bf16 v[60:63], v[170:173], v[218:221], v[60:63]
	v_mfma_f32_16x16x32_bf16 v[56:59], v[190:193], v[218:221], v[56:59]
	v_mfma_f32_16x16x32_bf16 v[44:47], v[170:173], v[226:229], v[44:47]
	v_mfma_f32_16x16x32_bf16 v[40:43], v[190:193], v[226:229], v[40:43]
	v_mfma_f32_16x16x32_bf16 v[28:31], v[170:173], v[234:237], v[28:31]
	v_mfma_f32_16x16x32_bf16 v[24:27], v[190:193], v[234:237], v[24:27]
	v_mfma_f32_16x16x32_bf16 v[12:15], v[170:173], v[242:245], v[12:15]
	v_mfma_f32_16x16x32_bf16 v[8:11], v[190:193], v[242:245], v[8:11]
	s_setprio 0
	s_setprio 1
	v_mfma_f32_16x16x32_bf16 v[52:55], v[194:197], v[214:217], v[52:55]
	v_mfma_f32_16x16x32_bf16 v[48:51], v[202:205], v[214:217], v[48:51]
	v_mfma_f32_16x16x32_bf16 v[36:39], v[194:197], v[222:225], v[36:39]
	v_mfma_f32_16x16x32_bf16 v[32:35], v[202:205], v[222:225], v[32:35]
	v_mfma_f32_16x16x32_bf16 v[20:23], v[194:197], v[230:233], v[20:23]
	v_mfma_f32_16x16x32_bf16 v[16:19], v[202:205], v[230:233], v[16:19]
	v_mfma_f32_16x16x32_bf16 v[4:7], v[194:197], v[238:241], v[4:7]
	v_mfma_f32_16x16x32_bf16 v[0:3], v[202:205], v[238:241], v[0:3]
	v_mfma_f32_16x16x32_bf16 v[52:55], v[198:201], v[218:221], v[52:55]
	v_mfma_f32_16x16x32_bf16 v[48:51], v[210:213], v[218:221], v[48:51]
	v_mfma_f32_16x16x32_bf16 v[36:39], v[198:201], v[226:229], v[36:39]
	v_mfma_f32_16x16x32_bf16 v[32:35], v[210:213], v[226:229], v[32:35]
	v_mfma_f32_16x16x32_bf16 v[20:23], v[198:201], v[234:237], v[20:23]
	v_mfma_f32_16x16x32_bf16 v[16:19], v[210:213], v[234:237], v[16:19]
	v_mfma_f32_16x16x32_bf16 v[4:7], v[198:201], v[242:245], v[4:7]
	v_mfma_f32_16x16x32_bf16 v[0:3], v[210:213], v[242:245], v[0:3]
	s_setprio 0
	s_add_u32 s4, s4, 0x100
	s_addc_u32 s5, s5, 0
	s_add_u32 s30, s30, 0x100
	s_addc_u32 s31, s31, 0
	s_cmp_ge_u32 s57, s29
	s_mov_b32 s36, s57
	s_barrier
	s_cbranch_scc0 .LBB0_1791
	s_and_b64 vcc, exec, s[16:17]
	s_cbranch_vccz .LBB0_1794
	s_barrier
